# speedup vs baseline: 1.0108x; 1.0108x over previous
; #define LAS __attribute__((address_space(3)))
; __device__ __forceinline__ unsigned cvt_pk_bf16(float lo, float hi) { unsigned r; asm("v_cvt_pk_bf16_f32 %0, %1, %2" : "=v"(r) : "v"(lo), "v"(hi)); return r; }
; __global__ void __launch_bounds__(512, 2) fwd_kernel(KP p) {
;     ...
;         for (int m = gw; m < M; m += NGW) {
;             const int s = m >> 13; const float* xr = (s < 4) ? p.in[I_XP] + (size_t)m * DM : p.in[I_XS] + (size_t)(m - 4 * SEQ) * DM;
;             f32x4 v[8]; float ss = 0.f;
; #pragma unroll
;             for (int j = 0; j < 8; ++j) { v[j] = *(const f32x4*)(xr + j * 256 + lane * 4); ss += (v[j].x * v[j].x + v[j].y * v[j].y) + (v[j].z * v[j].z + v[j].w * v[j].w); }
;             const float r = rsqrtf(wave_sum(ss) * (1.f / DM) + EPS);
; #pragma unroll
;             for (int j = 0; j < 8; ++j) { const int col = j * 256 + lane * 4; const f32x4 av = *(const LAS f32x4*)(a1 + s * DM + col), bv = *(const LAS f32x4*)(b1 + s * DM + col);
;                 const f32x4 h = v[j] * r * av + bv; u32x2 w; w.x = cvt_pk_bf16(h.x, h.y); w.y = cvt_pk_bf16(h.z, h.w); *(u32x2*)(Hb + (size_t)m * DM + col) = w; }
;         }
.LBB0_205:
	s_or_b64 exec, exec, s[0:1]
	v_and_b32_e32 v93, 63, v64
	s_andn2_b64 vcc, exec, s[92:93]
	v_lshlrev_b32_e32 v32, 2, v93
	s_mov_b64 s[46:47], s[16:17]
	s_waitcnt lgkmcnt(0)
	s_barrier
	s_cbranch_vccnz .LBB0_210
	s_lshr_b32 s98, s64, 6
	s_mul_i32 s100, s3, 6
	s_mul_i32 s101, s100, 24
	s_cmp_lt_u32 s98, 2
	s_cbranch_scc1 .Lp1_w01
	s_mul_i32 s99, s2, 6
	s_add_i32 s98, s98, s99
	s_sub_i32 s98, s98, 2
	s_sub_i32 s101, s101, 1
	s_min_i32 s101, s101, 0x9fff
	s_branch .Lp1_wset
.Lp1_w01:
	s_lshl_b32 s99, s2, 1
	s_add_i32 s98, s98, s99
	s_add_i32 s98, s98, s101
	s_lshl_b32 s100, s3, 1
	s_mov_b32 s101, 0x9fff
.Lp1_wset:
	s_mov_b32 s99, 0
	s_cmp_gt_i32 s98, s101
	s_cbranch_scc1 .LBB0_210
	v_mbcnt_lo_u32_b32 v0, -1, 0
	v_mbcnt_hi_u32_b32 v0, -1, v0
	v_and_b32_e32 v1, 64, v0
	v_add_u32_e32 v1, 64, v1
	v_xor_b32_e32 v2, 1, v0
	v_cmp_lt_i32_e32 vcc, v2, v1
	v_readlane_b32 s72, v254, 10
	s_ashr_i32 s91, s90, 31
	v_cndmask_b32_e32 v2, v0, v2, vcc
	v_lshlrev_b32_e32 v33, 2, v2
	v_xor_b32_e32 v2, 2, v0
	v_cmp_lt_i32_e32 vcc, v2, v1
	v_readlane_b32 s73, v254, 11
	s_ashr_i32 s95, s94, 31
	v_cndmask_b32_e32 v2, v0, v2, vcc
	v_lshlrev_b32_e32 v40, 2, v2
	v_xor_b32_e32 v2, 4, v0
	v_cmp_lt_i32_e32 vcc, v2, v1
	s_lshl_b64 s[6:7], s[98:99], 13
	v_readlane_b32 s74, v254, 12
	v_cndmask_b32_e32 v2, v0, v2, vcc
	v_lshlrev_b32_e32 v41, 2, v2
	v_xor_b32_e32 v2, 8, v0
	v_cmp_lt_i32_e32 vcc, v2, v1
	v_readlane_b32 s75, v254, 13
	s_mov_b64 s[16:17], s[72:73]
	v_cndmask_b32_e32 v2, v0, v2, vcc
	v_lshlrev_b32_e32 v42, 2, v2
	v_xor_b32_e32 v2, 16, v0
	v_cmp_lt_i32_e32 vcc, v2, v1
	v_mov_b32_e32 v35, 0
	v_lshlrev_b32_e32 v34, 3, v93
	v_cndmask_b32_e32 v2, v0, v2, vcc
	v_lshlrev_b32_e32 v43, 2, v2
	v_xor_b32_e32 v2, 32, v0
	v_cmp_lt_i32_e32 vcc, v2, v1
	s_add_u32 s6, s16, s6
	s_mov_b32 s1, 0
	v_cndmask_b32_e32 v0, v0, v2, vcc
	v_lshlrev_b32_e32 v44, 2, v0
	v_lshl_add_u32 v45, v93, 4, 0
	v_lshl_add_u64 v[36:37], s[70:71], 0, v[34:35]
	s_addc_u32 s7, s17, s7
	s_lshl_b32 s8, s100, 13
	s_mov_b32 s9, 0
	v_lshlrev_b32_e32 v34, 2, v32
	v_mov_b32_e32 v46, 0x358637bd
	s_mov_b64 s[24:25], s[98:99]
	v_readlane_b32 s76, v254, 14
	v_readlane_b32 s77, v254, 15
	v_readlane_b32 s78, v254, 16
	v_readlane_b32 s79, v254, 17
	v_readlane_b32 s80, v254, 18
	v_readlane_b32 s81, v254, 19
	v_readlane_b32 s82, v254, 20
	v_readlane_b32 s83, v254, 21
	v_readlane_b32 s84, v254, 22
	v_readlane_b32 s85, v254, 23
	v_readlane_b32 s86, v254, 24
	v_readlane_b32 s87, v254, 25
	s_mov_b64 s[18:19], s[74:75]
	s_branch .LBB0_208
.LBB0_207:
	global_load_dwordx4 v[24:27], v34, s[18:19]
	global_load_dwordx4 v[4:7], v34, s[18:19] offset:1024
	global_load_dwordx4 v[8:11], v34, s[18:19] offset:2048
	global_load_dwordx4 v[16:19], v34, s[18:19] offset:3072
	v_lshl_add_u64 v[0:1], s[18:19], 0, v[34:35]
	s_movk_i32 s0, 0x1000
	v_add_co_u32_e32 v12, vcc, s0, v0
	s_mov_b32 s0, 0x800000
	s_nop 0
	v_addc_co_u32_e32 v13, vcc, 0, v1, vcc
	global_load_dwordx4 v[20:23], v[12:13], off
	global_load_dwordx4 v[28:31], v[12:13], off offset:1024
	global_load_dwordx4 v[0:3], v[12:13], off offset:3072
	s_nop 0
	global_load_dwordx4 v[12:15], v[12:13], off offset:2048
	s_lshl_b64 s[18:19], s[26:27], 12
	s_add_u32 s24, s24, s100
	s_addc_u32 s25, s25, 0
	s_add_u32 s6, s6, s8
	s_addc_u32 s7, s7, s9
	s_cmp_gt_i32 s24, s101
	s_waitcnt vmcnt(7)
	v_mov_b32_e32 v48, v25
	s_waitcnt vmcnt(6)
	v_mov_b32_e32 v49, v5
	v_mov_b32_e32 v52, v27
	v_mov_b32_e32 v53, v7
	v_mov_b32_e32 v38, v24
	v_mov_b32_e32 v39, v4
	v_mov_b32_e32 v50, v26
	v_mov_b32_e32 v51, v6
	s_waitcnt vmcnt(5)
	v_pk_mul_f32 v[54:55], v[10:11], v[10:11]
	v_pk_mul_f32 v[56:57], v[8:9], v[8:9]
	v_pk_mul_f32 v[48:49], v[48:49], v[48:49]
	v_pk_mul_f32 v[52:53], v[52:53], v[52:53]
	v_pk_mov_b32 v[62:63], v[56:57], v[54:55] op_sel:[1,0]
	v_mov_b32_e32 v57, v55
	v_pk_fma_f32 v[38:39], v[38:39], v[38:39], v[48:49]
	v_pk_fma_f32 v[48:49], v[50:51], v[50:51], v[52:53]
	s_waitcnt vmcnt(4)
	v_mul_f32_e32 v58, v17, v17
	v_mul_f32_e32 v60, v19, v19
	v_pk_add_f32 v[50:51], v[62:63], v[56:57]
	v_pk_add_f32 v[38:39], v[38:39], v[48:49]
	v_pk_fma_f32 v[54:55], v[16:17], v[16:17], v[58:59] op_sel_hi:[1,1,0]
	v_pk_fma_f32 v[58:59], v[18:19], v[18:19], v[60:61] op_sel_hi:[1,1,0]
	s_waitcnt vmcnt(3)
	v_mul_f32_e32 v47, v20, v20
	v_mul_f32_e32 v63, v21, v21
	v_pk_add_f32 v[48:49], v[50:51], v[50:51] op_sel:[0,1] op_sel_hi:[1,0]
	v_pk_add_f32 v[38:39], v[38:39], v[38:39] op_sel:[0,1] op_sel_hi:[1,0]
	v_mul_f32_e32 v55, v22, v22
	v_mul_f32_e32 v59, v23, v23
	s_waitcnt vmcnt(2)
	v_pk_mul_f32 v[52:53], v[30:31], v[30:31]
	v_pk_mul_f32 v[56:57], v[28:29], v[28:29]
	v_mov_b32_e32 v49, v63
	v_mov_b32_e32 v39, v47
	v_pk_mov_b32 v[50:51], v[56:57], v[52:53] op_sel:[1,0]
	v_mov_b32_e32 v57, v53
	v_pk_add_f32 v[54:55], v[54:55], v[58:59]
	v_pk_add_f32 v[38:39], v[38:39], v[48:49]
	s_waitcnt vmcnt(0)
; #define LAS __attribute__((address_space(3)))
; __device__ __forceinline__ unsigned cvt_pk_bf16(float lo, float hi) { unsigned r; asm("v_cvt_pk_bf16_f32 %0, %1, %2" : "=v"(r) : "v"(lo), "v"(hi)); return r; }
; __global__ void __launch_bounds__(512, 2) fwd_kernel(KP p) {
;     ...
;             f32x4 v[8]; float ss = 0.f;
; #pragma unroll
;             for (int j = 0; j < 8; ++j) { v[j] = *(const f32x4*)(xr + j * 256 + lane * 4); ss += (v[j].x * v[j].x + v[j].y * v[j].y) + (v[j].z * v[j].z + v[j].w * v[j].w); }
;             const float r = rsqrtf(wave_sum(ss) * (1.f / DM) + EPS);
; #pragma unroll
;             for (int j = 0; j < 8; ++j) { const int col = j * 256 + lane * 4; const f32x4 av = *(const LAS f32x4*)(a1 + s * DM + col), bv = *(const LAS f32x4*)(b1 + s * DM + col);
;                 const f32x4 h = v[j] * r * av + bv; u32x2 w; w.x = cvt_pk_bf16(h.x, h.y); w.y = cvt_pk_bf16(h.z, h.w); *(u32x2*)(Hb + (size_t)m * DM + col) = w; }
	v_mul_f32_e32 v60, v13, v13
	v_mul_f32_e32 v62, v15, v15
	v_pk_add_f32 v[50:51], v[50:51], v[56:57]
	v_pk_add_f32 v[38:39], v[38:39], v[54:55]
	v_mul_f32_e32 v65, v0, v0
	v_mul_f32_e32 v66, v1, v1
	v_mul_f32_e32 v67, v2, v2
	v_mul_f32_e32 v68, v3, v3
	v_pk_fma_f32 v[52:53], v[12:13], v[12:13], v[60:61] op_sel_hi:[1,1,0]
	v_pk_fma_f32 v[60:61], v[14:15], v[14:15], v[62:63] op_sel_hi:[1,1,0]
	v_pk_add_f32 v[50:51], v[50:51], v[50:51] op_sel:[0,1] op_sel_hi:[1,0]
	v_pk_add_f32 v[38:39], v[38:39], v[38:39] op_sel:[0,1] op_sel_hi:[1,0]
	v_mov_b32_e32 v53, v67
	v_mov_b32_e32 v61, v68
	v_mov_b32_e32 v51, v66
	v_mov_b32_e32 v39, v65
	v_pk_add_f32 v[52:53], v[52:53], v[60:61]
	v_pk_add_f32 v[38:39], v[38:39], v[50:51]
	v_lshl_add_u32 v65, s20, 13, v45
	v_pk_add_f32 v[38:39], v[38:39], v[52:53]
	ds_read_b128 v[48:51], v65
	ds_read_b128 v[52:55], v65 offset:1024
	v_add_f32_e32 v38, v38, v39
	ds_bpermute_b32 v39, v33, v38
	s_waitcnt lgkmcnt(0)
	v_add_f32_e32 v38, v38, v39
	ds_bpermute_b32 v39, v40, v38
	s_waitcnt lgkmcnt(0)
	v_add_f32_e32 v38, v38, v39
	ds_bpermute_b32 v39, v41, v38
	s_waitcnt lgkmcnt(0)
	v_add_f32_e32 v38, v38, v39
	ds_bpermute_b32 v39, v42, v38
	s_waitcnt lgkmcnt(0)
	v_add_f32_e32 v47, v38, v39
	ds_bpermute_b32 v56, v43, v47
	v_lshl_add_u64 v[38:39], v[36:37], 0, s[18:19]
	s_waitcnt lgkmcnt(0)
	v_add_f32_e32 v47, v47, v56
	ds_bpermute_b32 v74, v44, v47
	ds_read_b128 v[56:59], v65 offset:40960
	ds_read_b128 v[60:63], v65 offset:41984
	ds_read_b128 v[66:69], v65 offset:2048
	ds_read_b128 v[70:73], v65 offset:3072
	s_waitcnt lgkmcnt(4)
	v_add_f32_e32 v47, v47, v74
	v_fmamk_f32 v47, v47, 0x3a000000, v46
	v_mul_f32_e32 v74, 0x4b800000, v47
	v_cmp_gt_f32_e32 vcc, s0, v47
	s_nop 1
	v_cndmask_b32_e32 v47, v47, v74, vcc
	v_rsq_f32_e32 v47, v47
	ds_read_b128 v[74:77], v65 offset:43008
	ds_read_b128 v[78:81], v65 offset:44032
	ds_read_b128 v[82:85], v65 offset:4096
	ds_read_b128 v[86:89], v65 offset:5120
	v_mul_f32_e32 v90, 0x45800000, v47
	v_cndmask_b32_e32 v90, v47, v90, vcc
	v_pk_mul_f32 v[24:25], v[90:91], v[24:25] op_sel_hi:[0,1]
	v_pk_mul_f32 v[26:27], v[90:91], v[26:27] op_sel_hi:[0,1]
	s_waitcnt lgkmcnt(7)
	v_pk_fma_f32 v[58:59], v[50:51], v[26:27], v[58:59]
	v_pk_fma_f32 v[56:57], v[48:49], v[24:25], v[56:57]
	ds_read_b128 v[24:27], v65 offset:45056
	ds_read_b128 v[48:51], v65 offset:46080
	v_pk_mul_f32 v[4:5], v[90:91], v[4:5] op_sel_hi:[0,1]
	v_pk_mul_f32 v[6:7], v[90:91], v[6:7] op_sel_hi:[0,1]
	v_pk_mul_f32 v[8:9], v[90:91], v[8:9] op_sel_hi:[0,1]
	v_pk_mul_f32 v[10:11], v[90:91], v[10:11] op_sel_hi:[0,1]
	v_pk_mul_f32 v[20:21], v[90:91], v[20:21] op_sel_hi:[0,1]
	s_waitcnt lgkmcnt(8)
	v_pk_fma_f32 v[6:7], v[54:55], v[6:7], v[62:63]
	v_pk_fma_f32 v[4:5], v[52:53], v[4:5], v[60:61]
	v_pk_mul_f32 v[16:17], v[90:91], v[16:17] op_sel_hi:[0,1]
	v_pk_mul_f32 v[18:19], v[90:91], v[18:19] op_sel_hi:[0,1]
	v_pk_mul_f32 v[22:23], v[90:91], v[22:23] op_sel_hi:[0,1]
	v_pk_mul_f32 v[28:29], v[90:91], v[28:29] op_sel_hi:[0,1]
	s_waitcnt lgkmcnt(5)
	v_pk_fma_f32 v[10:11], v[68:69], v[10:11], v[76:77]
	v_pk_fma_f32 v[8:9], v[66:67], v[8:9], v[74:75]
	s_waitcnt lgkmcnt(1)
	v_pk_fma_f32 v[20:21], v[82:83], v[20:21], v[24:25]
	v_cvt_pk_bf16_f32 v24, v56, v57
	v_cvt_pk_bf16_f32 v25, v58, v59
	v_cvt_pk_bf16_f32 v4, v4, v5
	v_cvt_pk_bf16_f32 v5, v6, v7
	v_cvt_pk_bf16_f32 v6, v8, v9
	v_cvt_pk_bf16_f32 v7, v10, v11
	v_pk_mul_f32 v[30:31], v[90:91], v[30:31] op_sel_hi:[0,1]
	v_pk_fma_f32 v[18:19], v[72:73], v[18:19], v[80:81]
	v_pk_fma_f32 v[16:17], v[70:71], v[16:17], v[78:79]
	v_pk_fma_f32 v[22:23], v[84:85], v[22:23], v[26:27]
	v_cvt_pk_bf16_f32 v8, v16, v17
	v_cvt_pk_bf16_f32 v9, v18, v19
	v_cvt_pk_bf16_f32 v10, v20, v21
	v_pk_mul_f32 v[20:21], v[90:91], v[12:13] op_sel_hi:[0,1]
	v_cvt_pk_bf16_f32 v11, v22, v23
	global_store_dwordx2 v[38:39], v[24:25], off
	global_store_dwordx2 v[38:39], v[4:5], off offset:512
	global_store_dwordx2 v[38:39], v[6:7], off offset:1024
	global_store_dwordx2 v[38:39], v[8:9], off offset:1536
	global_store_dwordx2 v[38:39], v[10:11], off offset:2048
	s_waitcnt lgkmcnt(0)
	v_pk_fma_f32 v[6:7], v[86:87], v[28:29], v[48:49]
	v_pk_fma_f32 v[4:5], v[88:89], v[30:31], v[50:51]
	v_cvt_pk_bf16_f32 v6, v6, v7
	v_pk_mul_f32 v[22:23], v[90:91], v[14:15] op_sel_hi:[0,1]
	v_cvt_pk_bf16_f32 v7, v4, v5
	global_store_dwordx2 v[38:39], v[6:7], off offset:2560
	ds_read_b128 v[4:7], v65 offset:6144
	ds_read_b128 v[8:11], v65 offset:47104
	ds_read_b128 v[12:15], v65 offset:7168
	ds_read_b128 v[16:19], v65 offset:48128
	v_pk_mul_f32 v[0:1], v[90:91], v[0:1] op_sel_hi:[0,1]
	v_pk_mul_f32 v[2:3], v[90:91], v[2:3] op_sel_hi:[0,1]
	s_waitcnt lgkmcnt(2)
	v_pk_fma_f32 v[4:5], v[4:5], v[20:21], v[8:9]
	s_waitcnt lgkmcnt(0)
	v_pk_fma_f32 v[0:1], v[12:13], v[0:1], v[16:17]
	v_pk_fma_f32 v[6:7], v[6:7], v[22:23], v[10:11]
	v_cvt_pk_bf16_f32 v4, v4, v5
	v_pk_fma_f32 v[2:3], v[14:15], v[2:3], v[18:19]
	v_cvt_pk_bf16_f32 v5, v6, v7
	global_store_dwordx2 v[38:39], v[4:5], off offset:3072
	v_cvt_pk_bf16_f32 v0, v0, v1
	v_cvt_pk_bf16_f32 v1, v2, v3
	global_store_dwordx2 v[38:39], v[0:1], off offset:3584
	s_cbranch_scc1 .LBB0_210

; __device__ __forceinline__ void attn_unit(const bf16_t* __restrict__ Qb, const bf16_t* __restrict__ Kh, const bf16_t* __restrict__ Vh, bf16_t* __restrict__ Ob, float* __restrict__ ssq, char* lds, LAS unsigned char* ldsl, ...
;   const int wid = tid >> 6, lane = tid & 63, r32 = lane & 31, hi = lane >> 5;
;   char* V_lds = lds; char* K_lds = lds + 2 * SHM_V;
;   float* ws = (float*)(lds + 2 * SHM_V + 2 * SHM_K) + wid * 64; float* li_l = ws; float* al_l = ws + 32;
;   if (wid >= 4) __builtin_amdgcn_s_setprio(1);
;   float m_reg = -1e30f, l_reg = 0; f32x16 o[4]; bf16x8 qr[12];
;   char* qrope = lds + SHM_QR + wid * 4096 + lane * 16;
;   const bf16_t* Qw = Qb + (long)(wid * QBLK + r32) * QCOLS + hi * 8;
; #pragma unroll
;   for (int d0 = 0; d0 < 12; ++d0) qr[d0] = *reinterpret_cast<const bf16x8*>(Qw + d0 * 16);
;   {
;     float ss = 0.f;
; #pragma unroll
;     for (int d0 = 0; d0 < 12; ++d0) { float f[8]; unpack8(__builtin_bit_cast(u32x4, qr[d0]), f);
; #pragma unroll
;       for (int e = 0; e < 8; ++e) ss += f[e] * f[e]; }
;     { auto rr = __builtin_amdgcn_permlane32_swap(__float_as_uint(ss), __float_as_uint(ss), false, false); ss = __uint_as_float(rr[0]) + __uint_as_float(rr[1]); }
;     const float rq = rsqrtf(ss * (1.f / DQK) + EPS);
; #pragma unroll
;     for (int d0 = 0; d0 < 8; ++d0) { float f[8]; unpack8(__builtin_bit_cast(u32x4, qr[d0]), f); const float* gp = qg + d0 * 16 + hi * 8;
; #pragma unroll
;       for (int e = 0; e < 8; ++e) f[e] *= rq * gp[e];
;       qr[d0] = __builtin_bit_cast(bf16x8, pack8(f)); }
;     const int pos = pos0 + wid * QBLK + r32;
; #pragma unroll
;     for (int dd = 0; dd < 2; ++dd) { float x1[8], x2[8], y1[8], y2[8]; unpack8(__builtin_bit_cast(u32x4, qr[8 + dd]), x1); unpack8(__builtin_bit_cast(u32x4, qr[10 + dd]), x2);
;       const float* g1 = qg + 128 + dd * 16 + hi * 8; const float* g2 = g1 + 32; const float* cp_ = ropec + pos * 32 + dd * 16 + hi * 8; const float* sp_ = ropes + pos * 32 + dd * 16 + hi * 8;
; #pragma unroll
;       for (int e = 0; e < 8; ++e) { const float a = x1[e] * rq * g1[e], b = x2[e] * rq * g2[e]; y1[e] = a * cp_[e] - b * sp_[e]; y2[e] = b * cp_[e] + a * sp_[e]; }
;       *(u32x4*)(qrope + dd * 1024) = pack8(y1); *(u32x4*)(qrope + (2 + dd) * 1024) = pack8(y2); }
;   }
;   unsigned kgo[3], vgo[2];
; #pragma unroll
.LBB0_997:
	s_cmp_lt_i32 s14, 7
	s_cselect_b64 s[0:1], -1, 0
	s_cmp_gt_i32 s15, 6
	s_cselect_b64 s[4:5], -1, 0
	s_and_b64 s[96:97], s[0:1], s[4:5]
	s_andn2_b64 vcc, exec, s[96:97]
	s_cbranch_vccnz .LBB0_1063
	s_mov_b32 s0, 0
	s_cmpk_lg_i32 s3, 0x100
	v_mbcnt_lo_u32_b32 v0, -1, s0
	v_mbcnt_hi_u32_b32 v172, -1, v0
	v_add_u32_e32 v173, s64, v172
	v_ashrrev_i32_e32 v1, 6, v173
	v_and_b32_e32 v2, 31, v172
	v_lshlrev_b32_e32 v175, 5, v1
	v_or_b32_e32 v176, v175, v2
	s_movk_i32 s0, 0xc00
	v_and_b32_e32 v174, 63, v172
	v_mad_i64_i32 v[160:161], s[0:1], v176, s0, 0
	s_cselect_b64 s[82:83], -1, 0
	v_lshlrev_b32_e32 v5, 4, v174
	s_add_i32 s0, 0, 0x14800
	v_lshlrev_b32_e32 v7, 10, v1
	v_lshl_add_u32 v6, v1, 12, s0
	v_or_b32_e32 v8, v7, v5
	s_mov_b32 s0, 0x2aaaaaab
	v_mul_hi_i32 v9, v8, s0
	v_lshrrev_b32_e32 v10, 31, v9
	v_ashrrev_i32_e32 v9, 6, v9
	v_add_u32_e32 v9, v9, v10
	v_mul_i32_i24_e32 v10, 0x180, v9
	v_lshlrev_b32_e32 v9, 3, v9
	v_sub_u32_e32 v11, v8, v10
	v_and_b32_e32 v9, 0x70, v9
	v_xad_u32 v177, v9, v11, v10
	v_add_u32_e32 v9, 0x2000, v8
	v_mul_hi_i32 v10, v9, s0
	v_lshrrev_b32_e32 v11, 31, v10
	v_ashrrev_i32_e32 v10, 6, v10
	v_add_u32_e32 v10, v10, v11
	v_mul_i32_i24_e32 v11, 0x180, v10
	v_lshlrev_b32_e32 v10, 3, v10
	v_sub_u32_e32 v9, v9, v11
	v_and_b32_e32 v10, 0x70, v10
	v_add_u32_e32 v8, 0x4000, v8
	v_xad_u32 v178, v10, v9, v11
	v_mul_hi_i32 v9, v8, s0
	v_lshrrev_b32_e32 v10, 31, v9
	v_ashrrev_i32_e32 v9, 6, v9
	v_add_u32_e32 v9, v9, v10
	v_mul_i32_i24_e32 v10, 0x180, v9
	v_lshlrev_b32_e32 v9, 3, v9
	v_sub_u32_e32 v8, v8, v10
	v_and_b32_e32 v9, 0x70, v9
	v_xad_u32 v179, v9, v8, v10
	v_lshlrev_b32_e32 v8, 3, v174
	v_bfe_u32 v9, v173, 2, 2
	v_lshrrev_b32_e32 v10, 1, v173
	v_ashrrev_i32_e32 v12, 8, v7
	v_and_b32_e32 v162, 32, v172
	v_and_or_b32 v9, v10, 8, v9
	v_and_b32_e32 v10, 64, v173
	v_and_b32_e32 v11, 24, v8
	v_and_b32_e32 v13, 0xfffff0, v12
	v_lshrrev_b32_e32 v12, 1, v12
	v_or3_b32 v10, v162, v10, v11
	v_and_b32_e32 v12, 4, v12
	v_lshlrev_b32_e32 v10, 1, v10
	v_or3_b32 v12, v13, v12, v9
	v_lshl_or_b32 v180, v12, 8, v10
	v_add_u32_e32 v12, 0x2000, v7
	v_ashrrev_i32_e32 v12, 8, v12
	v_and_b32_e32 v13, 0xfffff0, v12
	v_lshrrev_b32_e32 v12, 1, v12
	v_and_b32_e32 v12, 4, v12
	v_or3_b32 v9, v13, v12, v9
	v_lshl_or_b32 v181, v9, 8, v10
	v_lshlrev_b32_e32 v9, 1, v172
	s_waitcnt lgkmcnt(0)
	v_bfe_u32 v3, v172, 5, 1
	v_and_b32_e32 v9, 32, v9
	s_movk_i32 s0, 0xc0
	v_lshlrev_b32_e32 v12, 3, v172
	v_add_u32_e32 v182, 0, v7
	v_and_or_b32 v7, v5, s0, v9
	v_lshlrev_b32_e32 v9, 4, v3
	v_and_b32_e32 v13, 0x70, v12
	s_movk_i32 s1, 0x180
	v_bitop3_b32 v20, v9, v13, s0 bitop3:0x36
	s_movk_i32 s0, 0xe0
	v_mad_u32_u24 v14, v2, s1, 0
	s_movk_i32 s1, 0x60
	v_bitop3_b32 v21, v9, v13, s0 bitop3:0x36
	s_movk_i32 s0, 0x120
	s_and_b32 s26, s2, 7
	s_ashr_i32 s27, s2, 3
	s_add_i32 s43, 0, 0x14000
	v_bitop3_b32 v17, v9, v13, s1 bitop3:0x36
	s_movk_i32 s1, 0x80
	v_bitop3_b32 v23, v9, v13, s0 bitop3:0x36
	s_movk_i32 s0, 0x140
	s_movk_i32 s4, 0x100
	v_bitop3_b32 v18, v9, v13, s1 bitop3:0x36
	s_movk_i32 s1, 0xa0
	v_bitop3_b32 v24, v9, v13, s0 bitop3:0x36
	s_movk_i32 s0, 0x160
	s_cmp_lg_u32 0, -1
	v_and_b32_e32 v8, 0x100, v8
	v_bitop3_b32 v15, v9, v13, 32 bitop3:0x36
	v_bitop3_b32 v16, v9, v13, 64 bitop3:0x36
	v_bitop3_b32 v19, v9, v13, s1 bitop3:0x36
	v_bitop3_b32 v22, v9, v13, s4 bitop3:0x36
	v_bitop3_b32 v13, v9, v13, s0 bitop3:0x36
	s_cselect_b32 s0, 0, 0
	v_or3_b32 v7, v7, v8, v11
	s_addk_i32 s0, 0x4000
	v_add_u32_e32 v194, s0, v7
	s_movk_i32 s0, 0x2200
	v_and_b32_e32 v0, 0x3fffffc0, v173
	v_cmp_lt_i32_e64 s[38:39], 3, v1
	v_lshrrev_b32_e32 v25, 1, v172
	v_bfe_u32 v26, v172, 1, 3
	v_mul_lo_u32 v1, v1, s0
	v_lshl_add_u32 v4, v0, 2, s43
	v_mul_u32_u24_e32 v10, 0x180, v2
	v_bitop3_b32 v25, v3, v25, 7 bitop3:0x78
	v_bitop3_b32 v27, v3, v26, 2 bitop3:0x36
	v_bitop3_b32 v28, v3, v26, 4 bitop3:0x36
	v_bitop3_b32 v26, v3, v26, 6 bitop3:0x36
	v_add_u32_e32 v195, 0, v1
	v_lshlrev_b32_e32 v0, 3, v3
	v_readlane_b32 s52, v254, 26
	s_movk_i32 s5, 0x70
	v_lshl_or_b32 v25, v25, 4, v10
	v_lshl_or_b32 v27, v27, 4, v10
	v_lshl_or_b32 v28, v28, 4, v10
	v_lshl_or_b32 v10, v26, 4, v10
	v_add_u32_e32 v184, 0, v7
	v_lshl_add_u32 v185, v2, 2, v4
	v_lshl_add_u32 v1, v2, 1, v195
	v_mul_u32_u24_e32 v2, 0x440, v3
	v_lshl_or_b32 v3, v3, 2, 1
	s_movk_i32 s28, 0x110
	v_mov_b32_e32 v7, 0x990
	v_mov_b32_e32 v163, 0
	v_readlane_b32 s56, v254, 30
	v_readlane_b32 s57, v254, 31
	v_readlane_b32 s64, v254, 38
	v_readlane_b32 s65, v254, 39
	v_bitop3_b32 v12, v9, v12, s5 bitop3:0x78
	v_add_u32_e32 v186, 0, v25
	v_add_u32_e32 v188, 0, v27
	v_add_u32_e32 v190, 0, v28
	v_add_u32_e32 v192, 0, v10
	v_add_u32_e32 v196, v4, v9
	v_mul_u32_u24_e32 v4, 0x110, v3
	v_mad_u32_u24 v3, v3, s28, v7
	v_lshlrev_b32_e32 v170, 1, v0
	v_mbcnt_lo_u32_b32 v0, -1, 0
	v_readlane_b32 s20, v255, 17
	s_mov_b32 s48, 0
	v_lshl_add_u64 v[164:165], s[56:57], 0, v[162:163]
	v_lshl_add_u64 v[166:167], s[76:77], 0, v[162:163]
	v_lshl_add_u64 v[168:169], s[78:79], 0, v[162:163]
	v_add_u32_e32 v183, 0xe000, v182
	v_cmp_gt_u32_e64 s[40:41], 32, v174
	v_add_u32_e32 v187, 0xe000, v186
	v_add_u32_e32 v189, 0xe000, v188
	v_add_u32_e32 v191, 0xe000, v190
	v_add_u32_e32 v193, 0xe000, v192
	v_mov_b32_e32 v197, 0x358637bd
	v_add_u32_e32 v198, v14, v12
	v_add_u32_e32 v199, v14, v15
	v_add_u32_e32 v201, v14, v16
	v_add_u32_e32 v202, v14, v17
	v_add_u32_e32 v203, v14, v18
	v_add_u32_e32 v204, v14, v19
	v_add_u32_e32 v205, v14, v20
	v_add_u32_e32 v206, v14, v21
	v_add_u32_e32 v207, v14, v22
	v_add_u32_e32 v208, v14, v23
	v_add_u32_e32 v209, v14, v24
	v_add_u32_e32 v210, v14, v13
	s_mov_b32 s29, 0x42ddb3d8
	s_mov_b32 s80, 0x3dd53b94
	s_mov_b64 s[94:95], 0x1dd0c000
	s_mov_b64 s[34:35], 0x25504000
	v_mov_b32_e32 v211, 0x3dd53b94
	s_mov_b64 s[64:65], 0x1dd12000
	s_mov_b64 s[36:37], 0x25508000
	v_add_u32_e32 v212, v1, v2
	v_add_u32_e32 v213, v1, v4
	v_add_u32_e32 v214, v1, v3
	v_add_u32_e32 v215, v6, v5
	v_mov_b32_e32 v216, 0xf149f2ca
	v_mbcnt_hi_u32_b32 v200, -1, v0
	s_mov_b32 s30, 0
	v_readlane_b32 s21, v255, 18
	s_waitcnt vmcnt(0)
	s_barrier
	v_readlane_b32 s53, v254, 27
	v_readlane_b32 s54, v254, 28
	v_readlane_b32 s55, v254, 29
	v_readlane_b32 s58, v254, 32
	v_readlane_b32 s59, v254, 33
	v_readlane_b32 s60, v254, 34
	v_readlane_b32 s61, v254, 35
	v_readlane_b32 s62, v254, 36
	v_readlane_b32 s63, v254, 37
	v_readlane_b32 s66, v254, 40
	v_readlane_b32 s67, v254, 41
	v_readfirstlane_b32 s98, v182
	s_branch .LBB0_1001

; __device__ __forceinline__ void unpack8(u32x4 w, float* f) { f[0] = bflo(w.x); f[1] = bfhi(w.x); f[2] = bflo(w.y); f[3] = bfhi(w.y); f[4] = bflo(w.z); f[5] = bfhi(w.z); f[6] = bflo(w.w); f[7] = bfhi(w.w); }
; __device__ __forceinline__ void attn_unit(const bf16_t* __restrict__ Qb, const bf16_t* __restrict__ Kh, const bf16_t* __restrict__ Vh, bf16_t* __restrict__ Ob, float* __restrict__ ssq, char* lds, LAS unsigned char* ldsl, ...
;     ...
;   if (wid >= 4) __builtin_amdgcn_s_setprio(1);
;   float m_reg = -1e30f, l_reg = 0; f32x16 o[4]; bf16x8 qr[12];
;   char* qrope = lds + SHM_QR + wid * 4096 + lane * 16;
;   const bf16_t* Qw = Qb + (long)(wid * QBLK + r32) * QCOLS + hi * 8;
; #pragma unroll
;   for (int d0 = 0; d0 < 12; ++d0) qr[d0] = *reinterpret_cast<const bf16x8*>(Qw + d0 * 16);
;   {
;     float ss = 0.f;
; #pragma unroll
;     for (int d0 = 0; d0 < 12; ++d0) { float f[8]; unpack8(__builtin_bit_cast(u32x4, qr[d0]), f);
; #pragma unroll
;       for (int e = 0; e < 8; ++e) ss += f[e] * f[e]; }
;     { auto rr = __builtin_amdgcn_permlane32_swap(__float_as_uint(ss), __float_as_uint(ss), false, false); ss = __uint_as_float(rr[0]) + __uint_as_float(rr[1]); }
.LBB0_1007:
	s_mov_b64 s[8:9], -1
	s_and_b64 vcc, exec, s[0:1]
	s_cbranch_vccz .LBB0_1000
	s_and_saveexec_b64 s[0:1], s[38:39]
	s_setprio 1
	s_or_b64 exec, exec, s[0:1]
	s_ashr_i32 s0, s6, 3
	s_ashr_i32 s1, s0, 31
	s_lshl_b32 s49, s7, 8
	s_and_b32 s8, s6, 7
	s_lshl_b64 s[0:1], s[0:1], 13
	s_ashr_i32 s4, s49, 31
	s_add_u32 s0, s0, s49
	s_addc_u32 s1, s1, s4
	s_mul_i32 s4, s1, 0xc00
	s_mul_hi_u32 s5, s0, 0xc00
	s_add_i32 s5, s5, s4
	s_mul_i32 s4, s0, 0xc00
	s_add_u32 s4, s22, s4
	s_addc_u32 s5, s23, s5
	s_mul_i32 s7, s8, 0x180
	s_add_u32 s4, s4, s7
	s_addc_u32 s5, s5, 0
	v_lshl_add_u64 v[0:1], s[4:5], 0, v[160:161]
	v_mov_b32_e32 v171, v163
	v_lshl_add_u64 v[4:5], v[0:1], 0, v[170:171]
	global_load_dwordx4 v[32:35], v[4:5], off
	global_load_dwordx4 v[40:43], v[4:5], off offset:32
	global_load_dwordx4 v[44:47], v[4:5], off offset:64
	global_load_dwordx4 v[48:51], v[4:5], off offset:96
	global_load_dwordx4 v[28:31], v[4:5], off offset:128
	global_load_dwordx4 v[24:27], v[4:5], off offset:160
	global_load_dwordx4 v[16:19], v[4:5], off offset:192
	global_load_dwordx4 v[20:23], v[4:5], off offset:224
	global_load_dwordx4 v[8:11], v[4:5], off offset:256
	global_load_dwordx4 v[0:3], v[4:5], off offset:288
	global_load_dwordx4 v[12:15], v[4:5], off offset:320
	s_nop 0
	global_load_dwordx4 v[4:7], v[4:5], off offset:352
	s_nop 0
	global_load_dwordx4 v[118:121], v[164:165], off offset:16
	global_load_dwordx4 v[122:125], v[164:165], off
	s_mov_b32 s4, 0x800000
	s_ashr_i32 s7, s6, 31
	s_mul_i32 s31, s6, 0x300000
	v_readlane_b32 s16, v255, 15
	v_add_u32_e32 v217, 0x8000, v182
	s_mul_hi_i32 s9, s6, 0x300000
	v_readlane_b32 s17, v255, 16
	s_add_u32 s24, s16, s31
	s_addc_u32 s25, s17, s9
	v_add_u32_e32 v218, 0xa000, v182
	v_add_u32_e32 v219, 0xc000, v182
	s_lshl_b64 s[90:91], s[6:7], 21
	s_add_u32 s92, s20, s90
	s_addc_u32 s93, s21, s91
	v_add_u32_e32 v220, 0x2000, v182
	v_readfirstlane_b32 s6, v183
	v_add_u32_e32 v221, 0x2000, v183
	v_add_u32_e32 v222, 0x4000, v183
	s_mov_b32 s50, s48
	s_mov_b32 s51, s48
	s_mov_b32 s52, s48
	s_mov_b32 s53, s48
	s_mov_b32 s54, s48
	s_mov_b32 s55, s48
	s_mov_b32 s56, s48
	s_mov_b32 s57, s48
	s_mov_b32 s58, s48
	s_mov_b32 s59, s48
	s_mov_b32 s60, s48
	s_mov_b32 s61, s48
	s_mov_b32 s62, s48
	s_mov_b32 s63, s48
	v_mov_b32_e32 v171, 0
	s_waitcnt vmcnt(13)
	v_and_b32_e32 v115, 0xffff0000, v32
	v_lshlrev_b32_e32 v116, 16, v32
	v_mul_f32_e32 v38, v115, v115
	v_lshlrev_b32_e32 v114, 16, v33
	v_fmac_f32_e32 v38, v116, v116
	v_and_b32_e32 v113, 0xffff0000, v33
	v_fmac_f32_e32 v38, v114, v114
	v_lshlrev_b32_e32 v112, 16, v34
	v_fmac_f32_e32 v38, v113, v113
	v_and_b32_e32 v111, 0xffff0000, v34
	v_fmac_f32_e32 v38, v112, v112
	v_lshlrev_b32_e32 v110, 16, v35
	v_fmac_f32_e32 v38, v111, v111
	v_and_b32_e32 v109, 0xffff0000, v35
	v_fmac_f32_e32 v38, v110, v110
	v_fmac_f32_e32 v38, v109, v109
	s_waitcnt vmcnt(12)
	v_lshlrev_b32_e32 v102, 16, v40
	v_and_b32_e32 v101, 0xffff0000, v40
	v_fmac_f32_e32 v38, v102, v102
	v_lshlrev_b32_e32 v100, 16, v41
	v_fmac_f32_e32 v38, v101, v101
	v_and_b32_e32 v99, 0xffff0000, v41
	v_fmac_f32_e32 v38, v100, v100
	v_lshlrev_b32_e32 v98, 16, v42
	v_fmac_f32_e32 v38, v99, v99
	v_and_b32_e32 v97, 0xffff0000, v42
	v_fmac_f32_e32 v38, v98, v98
	v_lshlrev_b32_e32 v96, 16, v43
	v_fmac_f32_e32 v38, v97, v97
	v_and_b32_e32 v95, 0xffff0000, v43
	v_fmac_f32_e32 v38, v96, v96
	v_fmac_f32_e32 v38, v95, v95
	s_waitcnt vmcnt(11)
	v_lshlrev_b32_e32 v94, 16, v44
	v_and_b32_e32 v93, 0xffff0000, v44
	v_fmac_f32_e32 v38, v94, v94
	v_lshlrev_b32_e32 v92, 16, v45
	v_fmac_f32_e32 v38, v93, v93
	v_and_b32_e32 v91, 0xffff0000, v45
	v_fmac_f32_e32 v38, v92, v92
	v_lshlrev_b32_e32 v90, 16, v46
	v_fmac_f32_e32 v38, v91, v91
	v_and_b32_e32 v89, 0xffff0000, v46
	v_fmac_f32_e32 v38, v90, v90
	v_lshlrev_b32_e32 v88, 16, v47
	v_fmac_f32_e32 v38, v89, v89
	v_and_b32_e32 v87, 0xffff0000, v47
	v_fmac_f32_e32 v38, v88, v88
	v_fmac_f32_e32 v38, v87, v87
	s_waitcnt vmcnt(10)
	v_lshlrev_b32_e32 v74, 16, v48
	v_and_b32_e32 v73, 0xffff0000, v48
	v_fmac_f32_e32 v38, v74, v74
	v_lshlrev_b32_e32 v72, 16, v49
	v_fmac_f32_e32 v38, v73, v73
	v_and_b32_e32 v71, 0xffff0000, v49
	v_fmac_f32_e32 v38, v72, v72
	v_lshlrev_b32_e32 v70, 16, v50
	v_fmac_f32_e32 v38, v71, v71
	v_and_b32_e32 v43, 0xffff0000, v50
	v_fmac_f32_e32 v38, v70, v70
	v_lshlrev_b32_e32 v37, 16, v51
	v_fmac_f32_e32 v38, v43, v43
	v_and_b32_e32 v33, 0xffff0000, v51
	v_fmac_f32_e32 v38, v37, v37
	v_fmac_f32_e32 v38, v33, v33
	s_waitcnt vmcnt(9)
	v_lshlrev_b32_e32 v79, 16, v28
	v_and_b32_e32 v78, 0xffff0000, v28
	v_fmac_f32_e32 v38, v79, v79
	v_lshlrev_b32_e32 v77, 16, v29
	v_fmac_f32_e32 v38, v78, v78
	v_and_b32_e32 v76, 0xffff0000, v29
	v_fmac_f32_e32 v38, v77, v77
	v_lshlrev_b32_e32 v75, 16, v30
	v_fmac_f32_e32 v38, v76, v76
	v_and_b32_e32 v30, 0xffff0000, v30
	v_fmac_f32_e32 v38, v75, v75
	v_lshlrev_b32_e32 v29, 16, v31
	v_fmac_f32_e32 v38, v30, v30
	v_and_b32_e32 v28, 0xffff0000, v31
	v_fmac_f32_e32 v38, v29, v29
	v_fmac_f32_e32 v38, v28, v28
	s_waitcnt vmcnt(8)
	v_lshlrev_b32_e32 v83, 16, v24
	v_and_b32_e32 v82, 0xffff0000, v24
	v_fmac_f32_e32 v38, v83, v83
	v_lshlrev_b32_e32 v81, 16, v25
	v_fmac_f32_e32 v38, v82, v82
	v_and_b32_e32 v80, 0xffff0000, v25
	v_fmac_f32_e32 v38, v81, v81
	v_lshlrev_b32_e32 v31, 16, v26
	v_fmac_f32_e32 v38, v80, v80
	v_and_b32_e32 v26, 0xffff0000, v26
	v_fmac_f32_e32 v38, v31, v31
	v_lshlrev_b32_e32 v25, 16, v27
	v_fmac_f32_e32 v38, v26, v26
	v_and_b32_e32 v24, 0xffff0000, v27
	v_fmac_f32_e32 v38, v25, v25
	v_fmac_f32_e32 v38, v24, v24
	s_waitcnt vmcnt(7)
; __device__ __forceinline__ u32x4 pack8(const float* f) { u32x4 w; w.x = cvt_pk_bf16(f[0], f[1]); w.y = cvt_pk_bf16(f[2], f[3]); w.z = cvt_pk_bf16(f[4], f[5]); w.w = cvt_pk_bf16(f[6], f[7]); return w; }
; __device__ __forceinline__ void unpack8(u32x4 w, float* f) { f[0] = bflo(w.x); f[1] = bfhi(w.x); f[2] = bflo(w.y); f[3] = bfhi(w.y); f[4] = bflo(w.z); f[5] = bfhi(w.z); f[6] = bflo(w.w); f[7] = bfhi(w.w); }
; __device__ __forceinline__ void attn_unit(const bf16_t* __restrict__ Qb, const bf16_t* __restrict__ Kh, const bf16_t* __restrict__ Vh, bf16_t* __restrict__ Ob, float* __restrict__ ssq, char* lds, LAS unsigned char* ldsl, ...
;     ...
;     float ss = 0.f;
; #pragma unroll
;     for (int d0 = 0; d0 < 12; ++d0) { float f[8]; unpack8(__builtin_bit_cast(u32x4, qr[d0]), f);
; #pragma unroll
;       for (int e = 0; e < 8; ++e) ss += f[e] * f[e]; }
;     { auto rr = __builtin_amdgcn_permlane32_swap(__float_as_uint(ss), __float_as_uint(ss), false, false); ss = __uint_as_float(rr[0]) + __uint_as_float(rr[1]); }
;     const float rq = rsqrtf(ss * (1.f / DQK) + EPS);
; #pragma unroll
;     for (int d0 = 0; d0 < 8; ++d0) { float f[8]; unpack8(__builtin_bit_cast(u32x4, qr[d0]), f); const float* gp = qg + d0 * 16 + hi * 8;
; #pragma unroll
;       for (int e = 0; e < 8; ++e) f[e] *= rq * gp[e];
;       qr[d0] = __builtin_bit_cast(bf16x8, pack8(f)); }
	v_lshlrev_b32_e32 v86, 16, v16
	v_and_b32_e32 v85, 0xffff0000, v16
	v_fmac_f32_e32 v38, v86, v86
	v_lshlrev_b32_e32 v84, 16, v17
	v_fmac_f32_e32 v38, v85, v85
	v_and_b32_e32 v27, 0xffff0000, v17
	v_fmac_f32_e32 v38, v84, v84
	v_lshlrev_b32_e32 v17, 16, v18
	v_fmac_f32_e32 v38, v27, v27
	v_and_b32_e32 v16, 0xffff0000, v18
	v_fmac_f32_e32 v38, v17, v17
	v_lshlrev_b32_e32 v103, 16, v19
	v_fmac_f32_e32 v38, v16, v16
	v_and_b32_e32 v18, 0xffff0000, v19
	v_fmac_f32_e32 v38, v103, v103
	v_fmac_f32_e32 v38, v18, v18
	s_waitcnt vmcnt(6)
	v_lshlrev_b32_e32 v108, 16, v20
	v_and_b32_e32 v107, 0xffff0000, v20
	v_fmac_f32_e32 v38, v108, v108
	v_lshlrev_b32_e32 v106, 16, v21
	v_fmac_f32_e32 v38, v107, v107
	v_and_b32_e32 v105, 0xffff0000, v21
	v_fmac_f32_e32 v38, v106, v106
	v_lshlrev_b32_e32 v104, 16, v22
	v_fmac_f32_e32 v38, v105, v105
	v_and_b32_e32 v21, 0xffff0000, v22
	v_fmac_f32_e32 v38, v104, v104
	v_lshlrev_b32_e32 v20, 16, v23
	v_fmac_f32_e32 v38, v21, v21
	v_and_b32_e32 v19, 0xffff0000, v23
	v_fmac_f32_e32 v38, v20, v20
	s_waitcnt vmcnt(5)
	v_lshlrev_b32_e32 v58, 16, v11
	v_and_b32_e32 v56, 0xffff0000, v11
	v_lshlrev_b32_e32 v62, 16, v10
	v_and_b32_e32 v60, 0xffff0000, v10
	s_waitcnt vmcnt(3)
	v_lshlrev_b32_e32 v11, 16, v12
	v_lshlrev_b32_e32 v10, 16, v8
	v_fmac_f32_e32 v38, v19, v19
	v_pk_mul_f32 v[136:137], v[10:11], v[10:11]
	v_and_b32_e32 v69, 0xffff0000, v12
	v_and_b32_e32 v68, 0xffff0000, v8
	v_lshlrev_b32_e32 v36, 16, v3
	v_and_b32_e32 v32, 0xffff0000, v3
	v_lshlrev_b32_e32 v67, 16, v13
	v_lshlrev_b32_e32 v66, 16, v9
	v_and_b32_e32 v64, 0xffff0000, v9
	v_add_f32_e32 v3, v136, v38
	v_pk_mul_f32 v[8:9], v[68:69], v[68:69]
	v_pk_mul_f32 v[132:133], v[66:67], v[66:67]
	v_and_b32_e32 v65, 0xffff0000, v13
	v_add_f32_e32 v3, v8, v3
	v_lshlrev_b32_e32 v63, 16, v14
	v_pk_mul_f32 v[134:135], v[64:65], v[64:65]
	v_add_f32_e32 v3, v132, v3
	v_pk_mul_f32 v[130:131], v[62:63], v[62:63]
	v_and_b32_e32 v61, 0xffff0000, v14
	v_add_f32_e32 v3, v134, v3
	v_lshlrev_b32_e32 v59, 16, v15
	v_and_b32_e32 v57, 0xffff0000, v15
	v_pk_mul_f32 v[14:15], v[60:61], v[60:61]
	v_add_f32_e32 v3, v130, v3
	v_pk_mul_f32 v[126:127], v[58:59], v[58:59]
	v_add_f32_e32 v3, v14, v3
	v_pk_mul_f32 v[128:129], v[56:57], v[56:57]
	v_add_f32_e32 v3, v126, v3
	s_waitcnt vmcnt(2)
	v_lshlrev_b32_e32 v55, 16, v4
	v_lshlrev_b32_e32 v54, 16, v0
	v_add_f32_e32 v8, v128, v3
	v_pk_mul_f32 v[12:13], v[54:55], v[54:55]
	v_and_b32_e32 v49, 0xffff0000, v4
	v_and_b32_e32 v48, 0xffff0000, v0
	v_add_lshl_u32 v40, v176, s49, 5
	v_lshlrev_b32_e32 v47, 16, v5
	v_lshlrev_b32_e32 v46, 16, v1
	v_and_b32_e32 v45, 0xffff0000, v5
	v_and_b32_e32 v44, 0xffff0000, v1
	v_add_f32_e32 v5, v12, v8
	v_pk_mul_f32 v[0:1], v[48:49], v[48:49]
	v_ashrrev_i32_e32 v41, 31, v40
	v_add_f32_e32 v0, v0, v5
	v_lshlrev_b64 v[40:41], 2, v[40:41]
	v_fmac_f32_e32 v0, v46, v46
	v_lshl_add_u64 v[52:53], v[166:167], 0, v[40:41]
	v_lshl_add_u64 v[50:51], v[168:169], 0, v[40:41]
	v_lshlrev_b32_e32 v40, 16, v2
	v_fmac_f32_e32 v0, v44, v44
	v_and_b32_e32 v38, 0xffff0000, v2
	v_fmac_f32_e32 v0, v40, v40
	v_fmac_f32_e32 v0, v38, v38
	v_fmac_f32_e32 v0, v36, v36
	v_fmac_f32_e32 v0, v32, v32
	v_add_f32_e32 v0, v137, v0
	v_add_f32_e32 v0, v9, v0
	v_add_f32_e32 v0, v133, v0
	v_add_f32_e32 v0, v135, v0
	v_add_f32_e32 v0, v131, v0
	v_add_f32_e32 v0, v15, v0
	v_add_f32_e32 v0, v127, v0
	v_add_f32_e32 v0, v129, v0
	v_and_b32_e32 v34, 0xffff0000, v7
	v_lshlrev_b32_e32 v35, 16, v7
	v_lshlrev_b32_e32 v41, 16, v6
	v_and_b32_e32 v39, 0xffff0000, v6
	v_mov_b32_e32 v6, v45
	v_mov_b32_e32 v7, v47
	v_add_f32_e32 v0, v13, v0
	v_pk_mul_f32 v[6:7], v[6:7], v[6:7]
	v_add_f32_e32 v0, v1, v0
	v_mov_b32_e32 v2, v39
	v_mov_b32_e32 v3, v41
	v_add_f32_e32 v0, v7, v0
	v_pk_mul_f32 v[2:3], v[2:3], v[2:3]
	v_add_f32_e32 v0, v6, v0
	v_add_f32_e32 v0, v3, v0
	v_pk_mul_f32 v[22:23], v[34:35], v[34:35]
	v_add_f32_e32 v0, v2, v0
	v_add_f32_e32 v0, v23, v0
	v_add_f32_e32 v0, v22, v0
	v_mov_b32_e32 v1, v0
	s_nop 1
	v_permlane32_swap_b32_e32 v0, v1
	v_add_f32_e32 v0, v0, v1
	v_fmamk_f32 v0, v0, 0x3baaaaab, v197
	v_cmp_gt_f32_e32 vcc, s4, v0
	v_mul_f32_e32 v1, 0x4b800000, v0
	v_readfirstlane_b32 s4, v217
	v_cndmask_b32_e32 v0, v0, v1, vcc
	v_rsq_f32_e32 v0, v0
	s_mov_b32 m0, s4
	v_readfirstlane_b32 s4, v218
	s_mov_b32 s49, s48
	v_mul_f32_e32 v1, 0x45800000, v0
	v_cndmask_b32_e32 v42, v0, v1, vcc
	s_waitcnt vmcnt(0)
	v_mul_f32_e32 v0, v122, v42
	v_mul_f32_e32 v1, v123, v42
	v_mul_f32_e32 v2, v124, v42
	v_mul_f32_e32 v3, v125, v42
	v_mul_f32_e32 v4, v118, v42
	v_mul_f32_e32 v5, v119, v42
	v_mul_f32_e32 v6, v120, v42
	v_mul_f32_e32 v7, v121, v42
	v_mul_f32_e32 v0, v0, v116
	v_mul_f32_e32 v1, v1, v115
	v_mul_f32_e32 v2, v2, v114
	v_mul_f32_e32 v3, v3, v113
	v_mul_f32_e32 v4, v4, v112
	v_mul_f32_e32 v5, v5, v111
	v_mul_f32_e32 v6, v6, v110
	v_mul_f32_e32 v7, v7, v109
	v_cvt_pk_bf16_f32 v128, v0, v1
	v_cvt_pk_bf16_f32 v129, v2, v3
	v_cvt_pk_bf16_f32 v130, v4, v5
	v_cvt_pk_bf16_f32 v131, v6, v7
	global_load_dwordx4 v[0:3], v[164:165], off offset:80
	global_load_dwordx4 v[4:7], v[164:165], off offset:64
	v_pk_mul_f32 v[8:9], v[42:43], v[10:11] op_sel_hi:[0,1]
	v_pk_mul_f32 v[68:69], v[42:43], v[68:69] op_sel_hi:[0,1]
	s_waitcnt vmcnt(1)
	v_mul_f32_e32 v0, v42, v0
	s_waitcnt vmcnt(0)
	v_mul_f32_e32 v4, v42, v4
	v_mul_f32_e32 v5, v42, v5
	v_mul_f32_e32 v6, v42, v6
	v_mul_f32_e32 v7, v42, v7
	v_mul_f32_e32 v1, v42, v1
	v_mul_f32_e32 v2, v42, v2
	v_mul_f32_e32 v3, v42, v3
	v_mul_f32_e32 v4, v4, v102
	v_mul_f32_e32 v5, v5, v101
	v_mul_f32_e32 v6, v6, v100
	v_mul_f32_e32 v7, v7, v99
	v_mul_f32_e32 v0, v0, v98
	v_mul_f32_e32 v1, v1, v97
	v_mul_f32_e32 v2, v2, v96
	v_mul_f32_e32 v3, v3, v95
	v_cvt_pk_bf16_f32 v132, v4, v5
	v_cvt_pk_bf16_f32 v133, v6, v7
	v_cvt_pk_bf16_f32 v134, v0, v1
	v_cvt_pk_bf16_f32 v135, v2, v3
	global_load_dwordx4 v[0:3], v[164:165], off offset:144
	global_load_dwordx4 v[4:7], v[164:165], off offset:128
	s_waitcnt vmcnt(1)
; __device__ __forceinline__ u32x4 pack8(const float* f) { u32x4 w; w.x = cvt_pk_bf16(f[0], f[1]); w.y = cvt_pk_bf16(f[2], f[3]); w.z = cvt_pk_bf16(f[4], f[5]); w.w = cvt_pk_bf16(f[6], f[7]); return w; }
; __device__ __forceinline__ void unpack8(u32x4 w, float* f) { f[0] = bflo(w.x); f[1] = bfhi(w.x); f[2] = bflo(w.y); f[3] = bfhi(w.y); f[4] = bflo(w.z); f[5] = bfhi(w.z); f[6] = bflo(w.w); f[7] = bfhi(w.w); }
; __device__ __forceinline__ void attn_unit(const bf16_t* __restrict__ Qb, const bf16_t* __restrict__ Kh, const bf16_t* __restrict__ Vh, bf16_t* __restrict__ Ob, float* __restrict__ ssq, char* lds, LAS unsigned char* ldsl, ...
;     ...
;     for (int d0 = 0; d0 < 8; ++d0) { float f[8]; unpack8(__builtin_bit_cast(u32x4, qr[d0]), f); const float* gp = qg + d0 * 16 + hi * 8;
; #pragma unroll
;       for (int e = 0; e < 8; ++e) f[e] *= rq * gp[e];
;       qr[d0] = __builtin_bit_cast(bf16x8, pack8(f)); }
	v_mul_f32_e32 v0, v42, v0
	s_waitcnt vmcnt(0)
	v_mul_f32_e32 v4, v42, v4
	v_mul_f32_e32 v5, v42, v5
	v_mul_f32_e32 v6, v42, v6
	v_mul_f32_e32 v7, v42, v7
	v_mul_f32_e32 v1, v42, v1
	v_mul_f32_e32 v2, v42, v2
	v_mul_f32_e32 v3, v42, v3
	v_mul_f32_e32 v4, v4, v94
	v_mul_f32_e32 v5, v5, v93
	v_mul_f32_e32 v6, v6, v92
	v_mul_f32_e32 v7, v7, v91
	v_mul_f32_e32 v0, v0, v90
	v_mul_f32_e32 v1, v1, v89
	v_mul_f32_e32 v2, v2, v88
	v_mul_f32_e32 v3, v3, v87
	v_cvt_pk_bf16_f32 v136, v4, v5
	v_cvt_pk_bf16_f32 v137, v6, v7
	v_cvt_pk_bf16_f32 v138, v0, v1
	v_cvt_pk_bf16_f32 v139, v2, v3
	global_load_dwordx4 v[0:3], v[164:165], off offset:208
	global_load_dwordx4 v[4:7], v[164:165], off offset:192
	s_waitcnt vmcnt(1)
	v_mul_f32_e32 v0, v42, v0
	s_waitcnt vmcnt(0)
	v_mul_f32_e32 v4, v42, v4
	v_mul_f32_e32 v5, v42, v5
	v_mul_f32_e32 v6, v42, v6
	v_mul_f32_e32 v7, v42, v7
	v_mul_f32_e32 v1, v42, v1
	v_mul_f32_e32 v2, v42, v2
	v_mul_f32_e32 v3, v42, v3
	v_mul_f32_e32 v4, v4, v74
	v_mul_f32_e32 v5, v5, v73
	v_mul_f32_e32 v6, v6, v72
	v_mul_f32_e32 v7, v7, v71
	v_mul_f32_e32 v0, v0, v70
	v_mul_f32_e32 v1, v1, v43
	v_mul_f32_e32 v2, v2, v37
	v_mul_f32_e32 v3, v3, v33
	v_cvt_pk_bf16_f32 v156, v4, v5
	v_cvt_pk_bf16_f32 v157, v6, v7
	v_cvt_pk_bf16_f32 v158, v0, v1
	v_cvt_pk_bf16_f32 v159, v2, v3
	global_load_dwordx4 v[0:3], v[164:165], off offset:272
	global_load_dwordx4 v[4:7], v[164:165], off offset:256
	s_waitcnt vmcnt(1)
	v_mul_f32_e32 v0, v42, v0
	s_waitcnt vmcnt(0)
	v_mul_f32_e32 v4, v42, v4
	v_mul_f32_e32 v5, v42, v5
	v_mul_f32_e32 v6, v42, v6
	v_mul_f32_e32 v7, v42, v7
	v_mul_f32_e32 v1, v42, v1
	v_mul_f32_e32 v2, v42, v2
	v_mul_f32_e32 v3, v42, v3
	v_mul_f32_e32 v4, v4, v79
	v_mul_f32_e32 v5, v5, v78
	v_mul_f32_e32 v6, v6, v77
	v_mul_f32_e32 v7, v7, v76
	v_mul_f32_e32 v0, v0, v75
	v_mul_f32_e32 v1, v1, v30
	v_mul_f32_e32 v2, v2, v29
	v_mul_f32_e32 v3, v3, v28
	v_cvt_pk_bf16_f32 v152, v4, v5
	v_cvt_pk_bf16_f32 v153, v6, v7
	v_cvt_pk_bf16_f32 v154, v0, v1
	v_cvt_pk_bf16_f32 v155, v2, v3
	global_load_dwordx4 v[0:3], v[164:165], off offset:336
	global_load_dwordx4 v[4:7], v[164:165], off offset:320
	s_waitcnt vmcnt(1)
	v_mul_f32_e32 v0, v42, v0
	s_waitcnt vmcnt(0)
	v_mul_f32_e32 v4, v42, v4
	v_mul_f32_e32 v5, v42, v5
	v_mul_f32_e32 v6, v42, v6
	v_mul_f32_e32 v7, v42, v7
	v_mul_f32_e32 v1, v42, v1
	v_mul_f32_e32 v2, v42, v2
	v_mul_f32_e32 v3, v42, v3
	v_mul_f32_e32 v4, v4, v83
	v_mul_f32_e32 v5, v5, v82
	v_mul_f32_e32 v6, v6, v81
	v_mul_f32_e32 v7, v7, v80
	v_mul_f32_e32 v0, v0, v31
	v_mul_f32_e32 v1, v1, v26
	v_mul_f32_e32 v2, v2, v25
	v_mul_f32_e32 v3, v3, v24
	v_cvt_pk_bf16_f32 v148, v4, v5
	v_cvt_pk_bf16_f32 v149, v6, v7
	v_cvt_pk_bf16_f32 v150, v0, v1
	v_cvt_pk_bf16_f32 v151, v2, v3
	global_load_dwordx4 v[0:3], v[164:165], off offset:400
	global_load_dwordx4 v[4:7], v[164:165], off offset:384
	s_waitcnt vmcnt(1)
	v_mul_f32_e32 v0, v42, v0
	s_waitcnt vmcnt(0)
	v_mul_f32_e32 v4, v42, v4
	v_mul_f32_e32 v5, v42, v5
	v_mul_f32_e32 v6, v42, v6
	v_mul_f32_e32 v7, v42, v7
	v_mul_f32_e32 v1, v42, v1
	v_mul_f32_e32 v2, v42, v2
	v_mul_f32_e32 v3, v42, v3
	v_mul_f32_e32 v4, v4, v86
	v_mul_f32_e32 v5, v5, v85
	v_mul_f32_e32 v6, v6, v84
	v_mul_f32_e32 v7, v7, v27
	v_mul_f32_e32 v0, v0, v17
	v_mul_f32_e32 v1, v1, v16
	v_mul_f32_e32 v2, v2, v103
	v_mul_f32_e32 v3, v3, v18
	v_cvt_pk_bf16_f32 v144, v4, v5
	v_cvt_pk_bf16_f32 v145, v6, v7
	v_cvt_pk_bf16_f32 v146, v0, v1
	v_cvt_pk_bf16_f32 v147, v2, v3
	global_load_dwordx4 v[0:3], v[164:165], off offset:464
	global_load_dwordx4 v[4:7], v[164:165], off offset:448
	s_waitcnt vmcnt(1)
	v_mul_f32_e32 v0, v42, v0
	s_waitcnt vmcnt(0)
	v_mul_f32_e32 v4, v42, v4
	v_mul_f32_e32 v5, v42, v5
	v_mul_f32_e32 v6, v42, v6
	v_mul_f32_e32 v7, v42, v7
	v_mul_f32_e32 v1, v42, v1
	v_mul_f32_e32 v2, v42, v2
	v_mul_f32_e32 v3, v42, v3
	v_mul_f32_e32 v4, v4, v108
	v_mul_f32_e32 v5, v5, v107
	v_mul_f32_e32 v6, v6, v106
	v_mul_f32_e32 v7, v7, v105
	v_mul_f32_e32 v0, v0, v104
	v_mul_f32_e32 v1, v1, v21
	v_mul_f32_e32 v2, v2, v20
	v_mul_f32_e32 v3, v3, v19
	v_cvt_pk_bf16_f32 v140, v4, v5
	v_cvt_pk_bf16_f32 v141, v6, v7
	v_cvt_pk_bf16_f32 v142, v0, v1
	v_cvt_pk_bf16_f32 v143, v2, v3
	global_load_dwordx4 v[0:3], v[164:165], off offset:528
	global_load_dwordx4 v[16:19], v[164:165], off offset:512
	global_load_dwordx4 v[4:7], v[164:165], off offset:656
	global_load_dwordx4 v[20:23], v[164:165], off offset:640
	s_waitcnt vmcnt(2)
	v_mov_b32_e32 v10, v16
	s_waitcnt vmcnt(0)
	v_mov_b32_e32 v11, v20
	v_pk_mul_f32 v[70:71], v[8:9], v[10:11]
	global_load_dwordx4 v[8:11], v[52:53], off offset:16
	global_load_dwordx4 v[24:27], v[52:53], off
	global_load_dwordx4 v[12:15], v[50:51], off offset:16
	global_load_dwordx4 v[28:31], v[50:51], off
	v_mov_b32_e32 v20, v17
	v_pk_mul_f32 v[16:17], v[68:69], v[20:21]
	s_waitcnt vmcnt(2)
	v_mov_b32_e32 v72, v24
	s_waitcnt vmcnt(0)
; __device__ __forceinline__ u32x4 pack8(const float* f) { u32x4 w; w.x = cvt_pk_bf16(f[0], f[1]); w.y = cvt_pk_bf16(f[2], f[3]); w.z = cvt_pk_bf16(f[4], f[5]); w.w = cvt_pk_bf16(f[6], f[7]); return w; }
; __device__ __forceinline__ void unpack8(u32x4 w, float* f) { f[0] = bflo(w.x); f[1] = bfhi(w.x); f[2] = bflo(w.y); f[3] = bfhi(w.y); f[4] = bflo(w.z); f[5] = bfhi(w.z); f[6] = bflo(w.w); f[7] = bfhi(w.w); }
; __device__ __forceinline__ void attn_unit(const bf16_t* __restrict__ Qb, const bf16_t* __restrict__ Kh, const bf16_t* __restrict__ Vh, bf16_t* __restrict__ Ob, float* __restrict__ ssq, char* lds, LAS unsigned char* ldsl, ...
;     ...
; #pragma unroll
;     for (int dd = 0; dd < 2; ++dd) { float x1[8], x2[8], y1[8], y2[8]; unpack8(__builtin_bit_cast(u32x4, qr[8 + dd]), x1); unpack8(__builtin_bit_cast(u32x4, qr[10 + dd]), x2);
;       const float* g1 = qg + 128 + dd * 16 + hi * 8; const float* g2 = g1 + 32; const float* cp_ = ropec + pos * 32 + dd * 16 + hi * 8; const float* sp_ = ropes + pos * 32 + dd * 16 + hi * 8;
; #pragma unroll
;       for (int e = 0; e < 8; ++e) { const float a = x1[e] * rq * g1[e], b = x2[e] * rq * g2[e]; y1[e] = a * cp_[e] - b * sp_[e]; y2[e] = b * cp_[e] + a * sp_[e]; }
;       *(u32x4*)(qrope + dd * 1024) = pack8(y1); *(u32x4*)(qrope + (2 + dd) * 1024) = pack8(y2); }
	v_mov_b32_e32 v73, v28
	v_pk_mul_f32 v[72:73], v[70:71], v[72:73]
	s_nop 0
	v_sub_f32_e32 v33, v72, v73
	v_mov_b32_e32 v72, v28
	v_mov_b32_e32 v73, v24
	v_mov_b32_e32 v28, v25
	v_mov_b32_e32 v24, v29
	v_pk_mul_f32 v[20:21], v[16:17], v[28:29]
	v_pk_mul_f32 v[16:17], v[16:17], v[24:25]
	v_sub_f32_e32 v28, v20, v21
	v_add_f32_e32 v24, v17, v16
	v_pk_mul_f32 v[16:17], v[42:43], v[66:67] op_sel_hi:[0,1]
	v_mov_b32_e32 v20, v18
	v_mov_b32_e32 v21, v22
	v_pk_mul_f32 v[16:17], v[16:17], v[20:21]
	v_mov_b32_e32 v20, v26
	v_mov_b32_e32 v21, v30
	v_pk_mul_f32 v[20:21], v[16:17], v[20:21]
	v_mov_b32_e32 v22, v19
	v_sub_f32_e32 v25, v20, v21
	v_mov_b32_e32 v20, v30
	v_mov_b32_e32 v21, v26
	v_pk_mul_f32 v[16:17], v[16:17], v[20:21]
	v_mov_b32_e32 v30, v27
	v_add_f32_e32 v20, v17, v16
	v_pk_mul_f32 v[16:17], v[42:43], v[64:65] op_sel_hi:[0,1]
	v_pk_mul_f32 v[16:17], v[16:17], v[22:23]
	v_mov_b32_e32 v26, v31
	v_pk_mul_f32 v[18:19], v[16:17], v[30:31]
	v_pk_mul_f32 v[16:17], v[16:17], v[26:27]
	v_sub_f32_e32 v21, v18, v19
	v_add_f32_e32 v22, v17, v16
	v_pk_mul_f32 v[16:17], v[42:43], v[62:63] op_sel_hi:[0,1]
	v_mov_b32_e32 v18, v0
	v_mov_b32_e32 v19, v4
	v_pk_mul_f32 v[16:17], v[16:17], v[18:19]
	v_mov_b32_e32 v18, v8
	v_mov_b32_e32 v19, v12
	v_pk_mul_f32 v[18:19], v[16:17], v[18:19]
	v_mov_b32_e32 v4, v1
	v_sub_f32_e32 v23, v18, v19
	v_mov_b32_e32 v18, v12
	v_mov_b32_e32 v19, v8
	v_pk_mul_f32 v[16:17], v[16:17], v[18:19]
	v_mov_b32_e32 v12, v9
	v_add_f32_e32 v18, v17, v16
	v_pk_mul_f32 v[16:17], v[42:43], v[60:61] op_sel_hi:[0,1]
	v_pk_mul_f32 v[0:1], v[16:17], v[4:5]
	v_mov_b32_e32 v8, v13
	v_pk_mul_f32 v[4:5], v[0:1], v[12:13]
	v_pk_mul_f32 v[0:1], v[0:1], v[8:9]
	v_sub_f32_e32 v12, v4, v5
	v_add_f32_e32 v8, v1, v0
	v_pk_mul_f32 v[0:1], v[42:43], v[58:59] op_sel_hi:[0,1]
	v_mov_b32_e32 v4, v2
	v_mov_b32_e32 v5, v6
	v_pk_mul_f32 v[0:1], v[0:1], v[4:5]
	v_mov_b32_e32 v4, v10
	v_mov_b32_e32 v5, v14
	v_pk_mul_f32 v[4:5], v[0:1], v[4:5]
	v_mov_b32_e32 v6, v3
	v_sub_f32_e32 v9, v4, v5
	v_mov_b32_e32 v4, v14
	v_mov_b32_e32 v5, v10
	v_pk_mul_f32 v[0:1], v[0:1], v[4:5]
	v_mov_b32_e32 v14, v11
	v_add_f32_e32 v4, v1, v0
	v_pk_mul_f32 v[0:1], v[42:43], v[56:57] op_sel_hi:[0,1]
	v_pk_mul_f32 v[0:1], v[0:1], v[6:7]
	v_mov_b32_e32 v10, v15
	v_pk_mul_f32 v[2:3], v[0:1], v[14:15]
	v_pk_mul_f32 v[0:1], v[0:1], v[10:11]
	v_sub_f32_e32 v3, v2, v3
	v_pk_mul_f32 v[70:71], v[70:71], v[72:73]
	v_add_f32_e32 v5, v1, v0
	v_cvt_pk_bf16_f32 v0, v33, v28
	v_cvt_pk_bf16_f32 v1, v25, v21
	v_cvt_pk_bf16_f32 v2, v23, v12
	v_cvt_pk_bf16_f32 v3, v9, v3
	v_add_f32_e32 v37, v71, v70
	ds_write_b128 v215, v[0:3]
	v_cvt_pk_bf16_f32 v0, v37, v24
	v_cvt_pk_bf16_f32 v1, v20, v22
	v_cvt_pk_bf16_f32 v2, v18, v8
	v_cvt_pk_bf16_f32 v3, v4, v5
	ds_write_b128 v215, v[0:3] offset:2048
	global_load_dwordx4 v[0:3], v[164:165], off offset:592
	global_load_dwordx4 v[16:19], v[164:165], off offset:576
	global_load_dwordx4 v[4:7], v[164:165], off offset:720
	global_load_dwordx4 v[20:23], v[164:165], off offset:704
	v_pk_mul_f32 v[8:9], v[42:43], v[54:55] op_sel_hi:[0,1]
	v_mov_b32_e32 v37, v35
	v_mov_b32_e32 v33, v34
	s_waitcnt vmcnt(2)
	v_mov_b32_e32 v10, v16
	s_waitcnt vmcnt(0)
	v_mov_b32_e32 v11, v20
	v_pk_mul_f32 v[54:55], v[8:9], v[10:11]
	global_load_dwordx4 v[8:11], v[52:53], off offset:80
	global_load_dwordx4 v[24:27], v[52:53], off offset:64
	global_load_dwordx4 v[12:15], v[50:51], off offset:80
	global_load_dwordx4 v[28:31], v[50:51], off offset:64
	v_mov_b32_e32 v20, v17
	s_waitcnt vmcnt(2)
	v_mov_b32_e32 v50, v24
	s_waitcnt vmcnt(0)
	v_mov_b32_e32 v51, v28
	v_pk_mul_f32 v[50:51], v[54:55], v[50:51]
	s_nop 0
	v_sub_f32_e32 v43, v50, v51
	v_pk_mul_f32 v[48:49], v[42:43], v[48:49] op_sel_hi:[0,1]
	v_mov_b32_e32 v50, v28
	v_mov_b32_e32 v51, v24
	v_pk_mul_f32 v[16:17], v[48:49], v[20:21]
	v_mov_b32_e32 v28, v25
	v_mov_b32_e32 v24, v29
	v_pk_mul_f32 v[20:21], v[16:17], v[28:29]
	v_pk_mul_f32 v[16:17], v[16:17], v[24:25]
	v_sub_f32_e32 v28, v20, v21
	v_add_f32_e32 v24, v17, v16
	v_pk_mul_f32 v[16:17], v[42:43], v[46:47] op_sel_hi:[0,1]
	v_mov_b32_e32 v20, v18
	v_mov_b32_e32 v21, v22
	v_pk_mul_f32 v[16:17], v[16:17], v[20:21]
	v_mov_b32_e32 v20, v26
	v_mov_b32_e32 v21, v30
	v_pk_mul_f32 v[20:21], v[16:17], v[20:21]
	v_mov_b32_e32 v22, v19
	v_sub_f32_e32 v25, v20, v21
	v_mov_b32_e32 v20, v30
	v_mov_b32_e32 v21, v26
	v_pk_mul_f32 v[16:17], v[16:17], v[20:21]
	v_mov_b32_e32 v30, v27
	v_add_f32_e32 v20, v17, v16
	v_pk_mul_f32 v[16:17], v[42:43], v[44:45] op_sel_hi:[0,1]
	v_pk_mul_f32 v[16:17], v[16:17], v[22:23]
	v_mov_b32_e32 v26, v31
	v_pk_mul_f32 v[18:19], v[16:17], v[30:31]
	v_pk_mul_f32 v[16:17], v[16:17], v[26:27]
	v_sub_f32_e32 v21, v18, v19
	v_add_f32_e32 v22, v17, v16
	v_pk_mul_f32 v[16:17], v[42:43], v[40:41] op_sel_hi:[0,1]
	v_mov_b32_e32 v18, v0
	v_mov_b32_e32 v19, v4
	v_pk_mul_f32 v[16:17], v[16:17], v[18:19]
	v_mov_b32_e32 v18, v8
	v_mov_b32_e32 v19, v12
	v_pk_mul_f32 v[18:19], v[16:17], v[18:19]
	v_mov_b32_e32 v4, v1
	v_sub_f32_e32 v23, v18, v19
	v_mov_b32_e32 v18, v12
	v_mov_b32_e32 v19, v8
	v_pk_mul_f32 v[16:17], v[16:17], v[18:19]
	v_mov_b32_e32 v12, v9
	v_add_f32_e32 v18, v17, v16
	v_pk_mul_f32 v[16:17], v[42:43], v[38:39] op_sel_hi:[0,1]
	v_pk_mul_f32 v[0:1], v[16:17], v[4:5]
	v_mov_b32_e32 v8, v13
	v_pk_mul_f32 v[4:5], v[0:1], v[12:13]
	v_pk_mul_f32 v[0:1], v[0:1], v[8:9]
	v_sub_f32_e32 v12, v4, v5
	v_add_f32_e32 v8, v1, v0
	v_pk_mul_f32 v[0:1], v[42:43], v[36:37] op_sel_hi:[0,1]
	v_mov_b32_e32 v4, v2
	v_mov_b32_e32 v5, v6
	v_pk_mul_f32 v[0:1], v[0:1], v[4:5]
	v_mov_b32_e32 v4, v10
	v_mov_b32_e32 v5, v14
	v_pk_mul_f32 v[4:5], v[0:1], v[4:5]
	v_mov_b32_e32 v6, v3
	v_sub_f32_e32 v9, v4, v5
; #define DMA_K(t, b) do { const char* kt_ = (const char*)Kh + (size_t)(t) * (KVBLK * DQK * 2); _Pragma("unroll") for (int i_ = 0; i_ < 3; ++i_) { unsigned of_ = kgo[i_]; asm volatile("" : "+v"(of_)); \
;       __builtin_amdgcn_global_load_lds((const unsigned*)(kt_ + of_), (LAS unsigned*)(ldsl + 2 * SHM_V + (b) * SHM_K + (i_ * 8 + wid) * 1024), 16, 0, 0); } } while (0)
; #define DMA_V(t, b) do { const char* vt_ = (const char*)Vh + (size_t)(t) * (KVBLK * DV * 2); _Pragma("unroll") for (int i_ = 0; i_ < 2; ++i_) { unsigned of_ = vgo[i_]; asm volatile("" : "+v"(of_)); \
;       __builtin_amdgcn_global_load_lds((const unsigned*)(vt_ + of_), (LAS unsigned*)(ldsl + (b) * SHM_V + (i_ * 8 + wid) * 1024), 16, 0, 0); } } while (0)
; __device__ __forceinline__ void qkt(f32x16& p0, f32x16& p1, const char* Ks, const bf16x8* qr, const char* qrope, int r32, int hi) {
;   p0 = f32x16{}; p1 = f32x16{};
;   for (int d0 = 0; d0 < 8; ++d0) { int cb = (d0 * 16 + hi * 8) * 2;
;     bf16x8 b0 = *reinterpret_cast<const bf16x8*>(Ks + KSWZ(r32, cb));
;     bf16x8 b1 = *reinterpret_cast<const bf16x8*>(Ks + KSWZ(32 + r32, cb));
;     p0 = __builtin_amdgcn_mfma_f32_32x32x16_bf16(b0, qr[d0], p0, 0, 0, 0);
;     p1 = __builtin_amdgcn_mfma_f32_32x32x16_bf16(b1, qr[d0], p1, 0, 0, 0); }
;   for (int d0 = 8; d0 < 12; ++d0) { int cb = (d0 * 16 + hi * 8) * 2;
;     bf16x8 b0 = *reinterpret_cast<const bf16x8*>(Ks + KSWZ(r32, cb));
;     bf16x8 b1 = *reinterpret_cast<const bf16x8*>(Ks + KSWZ(32 + r32, cb));
;     bf16x8 qf = *reinterpret_cast<const bf16x8*>(qrope + (d0 - 8) * 1024);
;     p0 = __builtin_amdgcn_mfma_f32_32x32x16_bf16(b0, qf, p0, 0, 0, 0);
;     p1 = __builtin_amdgcn_mfma_f32_32x32x16_bf16(b1, qf, p1, 0, 0, 0); }
; }
; __device__ __forceinline__ void attn_unit(const bf16_t* __restrict__ Qb, const bf16_t* __restrict__ Kh, const bf16_t* __restrict__ Vh, bf16_t* __restrict__ Ob, float* __restrict__ ssq, char* lds, LAS unsigned char* ldsl, ...
;     ...
;   constexpr int NT = SEQ / KVBLK;
;   o[0] = f32x16{}; o[1] = f32x16{}; o[2] = f32x16{}; o[3] = f32x16{};
;   f32x16 pA0, pA1, pB0, pB1; float mnA, mnB, alA, alB; bf16x8 pa0, pa1, pa2, pa3;
;   DMA_K(0, 0); DMA_V(0, 0); DMA_K(1, 1);
;   WAIT_BAR();
;   qkt(pA0, pA1, K_lds, qr, qrope, r32, hi); partialSM(pA0, pA1, m_reg, mnA, alA);
	v_mov_b32_e32 v4, v14
	v_mov_b32_e32 v5, v10
	v_pk_mul_f32 v[0:1], v[0:1], v[4:5]
	v_mov_b32_e32 v14, v11
	v_add_f32_e32 v4, v1, v0
	v_pk_mul_f32 v[0:1], v[42:43], v[32:33] op_sel_hi:[0,1]
	v_pk_mul_f32 v[0:1], v[0:1], v[6:7]
	v_mov_b32_e32 v10, v15
	v_pk_mul_f32 v[2:3], v[0:1], v[14:15]
	v_pk_mul_f32 v[0:1], v[0:1], v[10:11]
	v_pk_mul_f32 v[50:51], v[54:55], v[50:51]
	v_sub_f32_e32 v3, v2, v3
	v_add_f32_e32 v5, v1, v0
	v_cvt_pk_bf16_f32 v0, v43, v28
	v_add_f32_e32 v50, v51, v50
	v_cvt_pk_bf16_f32 v1, v25, v21
	v_cvt_pk_bf16_f32 v2, v23, v12
	v_cvt_pk_bf16_f32 v3, v9, v3
	ds_write_b128 v215, v[0:3] offset:1024
	v_cvt_pk_bf16_f32 v0, v50, v24
	v_cvt_pk_bf16_f32 v1, v20, v22
	v_cvt_pk_bf16_f32 v2, v18, v8
	v_cvt_pk_bf16_f32 v3, v4, v5
	ds_write_b128 v215, v[0:3] offset:3072
	v_mov_b32_e32 v0, v177
	s_nop 0
	global_load_lds_dwordx4 v0, s[24:25]
	v_mov_b32_e32 v0, v178
	s_mov_b32 m0, s4
	v_readfirstlane_b32 s4, v219
	global_load_lds_dwordx4 v0, s[24:25]
	v_mov_b32_e32 v0, v179
	s_mov_b32 m0, s4
	v_readfirstlane_b32 s4, v182
	global_load_lds_dwordx4 v0, s[24:25]
	v_mov_b32_e32 v0, v180
	s_mov_b32 m0, s4
	v_readfirstlane_b32 s4, v220
	global_load_lds_dwordx4 v0, s[92:93]
	v_mov_b32_e32 v0, v181
	s_mov_b32 m0, s4
	s_add_u32 s4, s24, 0x6000
	global_load_lds_dwordx4 v0, s[92:93]
	v_mov_b32_e32 v0, v177
	s_addc_u32 s5, s25, 0
	s_mov_b32 m0, s6
	v_readfirstlane_b32 s6, v221
	global_load_lds_dwordx4 v0, s[4:5]
	v_mov_b32_e32 v0, v178
	s_mov_b32 m0, s6
	v_readfirstlane_b32 s6, v222
	global_load_lds_dwordx4 v0, s[4:5]
	v_mov_b32_e32 v0, v179
	s_mov_b32 m0, s6
	s_mov_b32 s24, -2
	global_load_lds_dwordx4 v0, s[4:5]
	s_waitcnt vmcnt(0) lgkmcnt(0)
	s_barrier
	ds_read_b128 v[16:19], v198 offset:32768
	ds_read_b128 v[20:23], v198 offset:45056
	s_waitcnt lgkmcnt(0)
	v_mfma_f32_32x32x16_bf16 v[32:47], v[16:19], v[128:131], 0
	ds_read_b128 v[48:51], v199 offset:32768
	ds_read_b128 v[52:55], v199 offset:45056
	v_mov_b64_e32 v[0:1], s[48:49]
	v_mov_b64_e32 v[14:15], s[62:63]
	v_mov_b64_e32 v[2:3], s[50:51]
	v_mov_b64_e32 v[4:5], s[52:53]
	v_mov_b64_e32 v[6:7], s[54:55]
	v_mov_b64_e32 v[8:9], s[56:57]
	v_mfma_f32_32x32x16_bf16 v[16:31], v[20:23], v[128:131], 0
	v_mov_b64_e32 v[10:11], s[58:59]
	v_mov_b64_e32 v[12:13], s[60:61]
	s_waitcnt lgkmcnt(0)
	v_mfma_f32_32x32x16_bf16 v[32:47], v[48:51], v[132:135], v[32:47]
	v_mfma_f32_32x32x16_bf16 v[16:31], v[52:55], v[132:135], v[16:31]
	ds_read_b128 v[48:51], v201 offset:32768
	ds_read_b128 v[52:55], v201 offset:45056
	s_waitcnt lgkmcnt(0)
	v_mfma_f32_32x32x16_bf16 v[32:47], v[48:51], v[136:139], v[32:47]
	v_mfma_f32_32x32x16_bf16 v[16:31], v[52:55], v[136:139], v[16:31]
	ds_read_b128 v[48:51], v202 offset:32768
	ds_read_b128 v[52:55], v202 offset:45056
	s_waitcnt lgkmcnt(0)
	v_mfma_f32_32x32x16_bf16 v[32:47], v[48:51], v[156:159], v[32:47]
	v_mfma_f32_32x32x16_bf16 v[16:31], v[52:55], v[156:159], v[16:31]
	ds_read_b128 v[48:51], v203 offset:32768
	ds_read_b128 v[52:55], v203 offset:45056
	s_waitcnt lgkmcnt(0)
	v_mfma_f32_32x32x16_bf16 v[32:47], v[48:51], v[152:155], v[32:47]
	v_mfma_f32_32x32x16_bf16 v[16:31], v[52:55], v[152:155], v[16:31]
	ds_read_b128 v[48:51], v204 offset:32768
	ds_read_b128 v[52:55], v204 offset:45056
	s_waitcnt lgkmcnt(0)
	v_mfma_f32_32x32x16_bf16 v[32:47], v[48:51], v[148:151], v[32:47]
	v_mfma_f32_32x32x16_bf16 v[16:31], v[52:55], v[148:151], v[16:31]
	ds_read_b128 v[48:51], v205 offset:32768
	ds_read_b128 v[52:55], v205 offset:45056
	s_waitcnt lgkmcnt(0)
	v_mfma_f32_32x32x16_bf16 v[32:47], v[48:51], v[144:147], v[32:47]
	v_mfma_f32_32x32x16_bf16 v[16:31], v[52:55], v[144:147], v[16:31]
	ds_read_b128 v[48:51], v206 offset:32768
	ds_read_b128 v[52:55], v206 offset:45056
	s_waitcnt lgkmcnt(0)
	v_mfma_f32_32x32x16_bf16 v[32:47], v[48:51], v[140:143], v[32:47]
	v_mfma_f32_32x32x16_bf16 v[16:31], v[52:55], v[140:143], v[16:31]
	ds_read_b128 v[48:51], v207 offset:32768
	ds_read_b128 v[52:55], v207 offset:45056
	ds_read_b128 v[56:59], v215
	s_waitcnt lgkmcnt(0)
	v_mfma_f32_32x32x16_bf16 v[32:47], v[48:51], v[56:59], v[32:47]
	v_mfma_f32_32x32x16_bf16 v[16:31], v[52:55], v[56:59], v[16:31]
	ds_read_b128 v[48:51], v208 offset:32768
	ds_read_b128 v[52:55], v208 offset:45056
	ds_read_b128 v[56:59], v215 offset:1024
	s_waitcnt lgkmcnt(0)
	v_mfma_f32_32x32x16_bf16 v[32:47], v[48:51], v[56:59], v[32:47]
	v_mfma_f32_32x32x16_bf16 v[16:31], v[52:55], v[56:59], v[16:31]
	ds_read_b128 v[48:51], v209 offset:32768
	ds_read_b128 v[52:55], v209 offset:45056
	ds_read_b128 v[56:59], v215 offset:2048
	s_waitcnt lgkmcnt(0)
	v_mfma_f32_32x32x16_bf16 v[32:47], v[48:51], v[56:59], v[32:47]
	v_mfma_f32_32x32x16_bf16 v[16:31], v[52:55], v[56:59], v[16:31]
	ds_read_b128 v[48:51], v210 offset:32768
	ds_read_b128 v[52:55], v210 offset:45056
	ds_read_b128 v[56:59], v215 offset:3072
	s_waitcnt vmcnt(0) lgkmcnt(0)
	s_barrier
; #define LAS __attribute__((address_space(3)))
; __device__ __forceinline__ int v_rd_base(int lane) { return ((lane & 3) << 3) | (((lane >> 2) & 3) << 6) | (((lane >> 4) & 1) << 5) | (((lane >> 5) & 1) << 8); }
; #define WAIT_BAR() do { asm volatile("s_waitcnt vmcnt(0) lgkmcnt(0)" ::: "memory"); __builtin_amdgcn_s_barrier(); asm volatile("" ::: "memory"); } while (0)
; __device__ __forceinline__ void partialSM(f32x16& p0, f32x16& p1, float& m_reg, float& mn, float& alpha) {
;   constexpr float C = SCALE * 1.4426950408889634f;
;   float pmax = p0[0]; for (int r = 1; r < 16; ++r) pmax = fmaxf(pmax, p0[r]); for (int r = 0; r < 16; ++r) pmax = fmaxf(pmax, p1[r]);
;   { auto rr = __builtin_amdgcn_permlane32_swap(__float_as_uint(pmax), __float_as_uint(pmax), false, false);
;     pmax = fmaxf(__uint_as_float(rr[0]), __uint_as_float(rr[1])); }
;   if (__builtin_expect(__all(pmax - m_reg <= THR / SCALE), 1)) { mn = m_reg; alpha = 1.f; }
;   else { mn = fmaxf(m_reg, pmax); alpha = __builtin_amdgcn_exp2f((m_reg - mn) * C); m_reg = mn; }
;   float mnC = -mn * C;
;   for (int r = 0; r < 16; ++r) p0[r] = fmaf(p0[r], C, mnC); for (int r = 0; r < 16; ++r) p1[r] = fmaf(p1[r], C, mnC);
;   for (int r = 0; r < 16; ++r) p0[r] = __builtin_amdgcn_exp2f(p0[r]);
; __device__ __forceinline__ void attn_unit(const bf16_t* __restrict__ Qb, const bf16_t* __restrict__ Kh, const bf16_t* __restrict__ Vh, bf16_t* __restrict__ Ob, float* __restrict__ ssq, char* lds, LAS unsigned char* ldsl, ...
;     ...
;   constexpr int NT = SEQ / KVBLK;
;   o[0] = f32x16{}; o[1] = f32x16{}; o[2] = f32x16{}; o[3] = f32x16{};
;   f32x16 pA0, pA1, pB0, pB1; float mnA, mnB, alA, alB; bf16x8 pa0, pa1, pa2, pa3;
;   DMA_K(0, 0); DMA_V(0, 0); DMA_K(1, 1);
;   WAIT_BAR();
;   qkt(pA0, pA1, K_lds, qr, qrope, r32, hi); partialSM(pA0, pA1, m_reg, mnA, alA);
;   WAIT_BAR();
;   int kx[4];
; #pragma unroll
;   for (int jj = 0; jj < 4; ++jj) kx[jj] = r32 * 384 + ((((2 * jj + hi) ^ ((r32 >> 1) & 7))) << 4);
;   const LAS char* kl0 = (const LAS char*)(ldsl + 2 * SHM_V); const LAS char* vl0 = (const LAS char*)(ldsl + v_rd_base(lane)); const LAS char* qrl = (const LAS char*)(ldsl + SHM_QR + wid * 4096 + lane * 16);
;     ...
;   for (int j = 0; j < NT - 2; j += 2) {
;     STEP(pA0, pA1, alA, pB0, pB1, mnB, alB, j, true, true);
	s_waitcnt lgkmcnt(0)
	v_mfma_f32_32x32x16_bf16 v[32:47], v[48:51], v[56:59], v[32:47]
	v_mfma_f32_32x32x16_bf16 v[16:31], v[52:55], v[56:59], v[16:31]
	s_nop 10
	v_max_f32_e32 v48, v33, v33
	v_max_f32_e32 v49, v32, v32
	v_max_f32_e32 v48, v49, v48
	v_max3_f32 v48, v48, v34, v35
	v_max3_f32 v48, v48, v36, v37
	v_max3_f32 v48, v48, v38, v39
	v_max3_f32 v48, v48, v40, v41
	v_max3_f32 v48, v48, v42, v43
	v_max3_f32 v48, v48, v44, v45
	v_max3_f32 v48, v48, v46, v47
	v_max3_f32 v48, v48, v16, v17
	v_max3_f32 v48, v48, v18, v19
	v_max3_f32 v48, v48, v20, v21
	v_max3_f32 v48, v48, v22, v23
	v_max3_f32 v48, v48, v24, v25
	v_max3_f32 v48, v48, v26, v27
	v_max3_f32 v48, v48, v28, v29
	v_max3_f32 v48, v48, v30, v31
	v_mov_b32_e32 v49, v48
	s_nop 1
	v_permlane32_swap_b32_e32 v48, v49
	v_max_f32_e32 v49, v49, v49
	v_max_f32_e32 v48, v48, v48
	v_max_f32_e32 v48, v48, v49
	v_add_f32_e32 v49, 0x7149f2ca, v48
	v_cmp_ge_f32_e32 vcc, s29, v49
	s_cmp_eq_u64 vcc, exec
	s_cselect_b64 vcc, -1, 0
	v_max_f32_e32 v48, 0xf149f2ca, v48
	v_cndmask_b32_e32 v228, v48, v216, vcc
	v_sub_f32_e32 v49, 0xf149f2ca, v48
	v_mul_f32_e32 v48, 0xbdd53b94, v228
	v_mul_f32_e32 v49, 0x3dd53b94, v49
	v_fmamk_f32 v32, v32, 0x3dd53b94, v48
	v_exp_f32_e32 v80, v32
	v_exp_f32_e32 v32, v49
	v_fmamk_f32 v33, v33, 0x3dd53b94, v48
	v_fmamk_f32 v34, v34, 0x3dd53b94, v48
	v_fmamk_f32 v35, v35, 0x3dd53b94, v48
	v_fmamk_f32 v36, v36, 0x3dd53b94, v48
	v_fmamk_f32 v37, v37, 0x3dd53b94, v48
	v_fmamk_f32 v38, v38, 0x3dd53b94, v48
	v_fmamk_f32 v39, v39, 0x3dd53b94, v48
	v_fmamk_f32 v40, v40, 0x3dd53b94, v48
	v_fmamk_f32 v41, v41, 0x3dd53b94, v48
	v_fmamk_f32 v42, v42, 0x3dd53b94, v48
	v_fmamk_f32 v43, v43, 0x3dd53b94, v48
	v_fmamk_f32 v44, v44, 0x3dd53b94, v48
	v_fmamk_f32 v45, v45, 0x3dd53b94, v48
	v_fmamk_f32 v46, v46, 0x3dd53b94, v48
	v_fmamk_f32 v47, v47, 0x3dd53b94, v48
	v_exp_f32_e32 v81, v33
	v_exp_f32_e32 v82, v34
	v_exp_f32_e32 v83, v35
	v_exp_f32_e32 v84, v36
	v_exp_f32_e32 v85, v37
	v_exp_f32_e32 v86, v38
	v_exp_f32_e32 v87, v39
	v_exp_f32_e32 v88, v40
	v_exp_f32_e32 v89, v41
	v_exp_f32_e32 v90, v42
	v_exp_f32_e32 v91, v43
	v_exp_f32_e32 v92, v44
	v_exp_f32_e32 v93, v45
	v_exp_f32_e32 v94, v46
	v_exp_f32_e32 v95, v47
	v_cndmask_b32_e64 v224, v32, 1.0, vcc
	v_pk_fma_f32 v[78:79], v[30:31], s[80:81], v[48:49] op_sel_hi:[1,0,0]
	v_pk_fma_f32 v[76:77], v[28:29], s[80:81], v[48:49] op_sel_hi:[1,0,0]
	v_pk_fma_f32 v[74:75], v[26:27], s[80:81], v[48:49] op_sel_hi:[1,0,0]
	v_pk_fma_f32 v[72:73], v[24:25], s[80:81], v[48:49] op_sel_hi:[1,0,0]
	v_pk_fma_f32 v[70:71], v[22:23], s[80:81], v[48:49] op_sel_hi:[1,0,0]
	v_pk_fma_f32 v[68:69], v[20:21], s[80:81], v[48:49] op_sel_hi:[1,0,0]
	v_pk_fma_f32 v[66:67], v[18:19], s[80:81], v[48:49] op_sel_hi:[1,0,0]
	v_pk_fma_f32 v[64:65], v[16:17], s[80:81], v[48:49] op_sel_hi:[1,0,0]
	v_mov_b64_e32 v[62:63], v[14:15]
	v_mov_b64_e32 v[46:47], v[14:15]
	v_mov_b64_e32 v[30:31], v[14:15]
	v_mov_b64_e32 v[60:61], v[12:13]
	v_mov_b64_e32 v[58:59], v[10:11]
	v_mov_b64_e32 v[56:57], v[8:9]
	v_mov_b64_e32 v[54:55], v[6:7]
	v_mov_b64_e32 v[52:53], v[4:5]
	v_mov_b64_e32 v[50:51], v[2:3]
	v_mov_b64_e32 v[48:49], v[0:1]
	v_mov_b64_e32 v[44:45], v[12:13]
	v_mov_b64_e32 v[42:43], v[10:11]
	v_mov_b64_e32 v[40:41], v[8:9]
	v_mov_b64_e32 v[38:39], v[6:7]
	v_mov_b64_e32 v[36:37], v[4:5]
	v_mov_b64_e32 v[34:35], v[2:3]
	v_mov_b64_e32 v[32:33], v[0:1]
	v_mov_b64_e32 v[28:29], v[12:13]
	v_mov_b64_e32 v[26:27], v[10:11]
	v_mov_b64_e32 v[24:25], v[8:9]
	v_mov_b64_e32 v[22:23], v[6:7]
	v_mov_b64_e32 v[20:21], v[4:5]
	v_mov_b64_e32 v[18:19], v[2:3]
	v_mov_b64_e32 v[16:17], v[0:1]
	v_add_u32_e32 v225, 0x4000, v182
	v_add_u32_e32 v226, 0x6000, v182
.LBB0_1011:
	ds_read_b128 v[230:233], v186 offset:57344
	ds_read_b128 v[234:237], v187 offset:12288
	s_add_u32 s4, s12, s31
	s_addc_u32 s5, s13, s9
	s_add_u32 s4, s4, 0x1dd0c000
	s_addc_u32 s5, s5, 0
	s_add_u32 s6, s12, s90
	s_addc_u32 s7, s13, s91
	s_add_u32 s6, s6, 0x25504000
	s_addc_u32 s7, s7, 0
	s_add_i32 m0, s98, 0x8000
	s_nop 0
	global_load_lds_dwordx4 v177, s[4:5]
	s_add_i32 m0, s98, 0xa000
	s_nop 0
	global_load_lds_dwordx4 v178, s[4:5]
	s_add_i32 m0, s98, 0xc000
	s_nop 0
	global_load_lds_dwordx4 v179, s[4:5]
	s_add_i32 m0, s98, 0x4000
	s_nop 0
	global_load_lds_dwordx4 v180, s[6:7]
	s_add_i32 m0, s98, 0x6000
	s_nop 0
	global_load_lds_dwordx4 v181, s[6:7]
	s_waitcnt lgkmcnt(0)
	ds_read_b128 v[244:247], v186 offset:57600
	ds_read_b128 v[248:251], v187 offset:12544
	ds_read_b128 v[238:241], v215
	v_exp_f32_e32 v64, v64
	v_exp_f32_e32 v65, v65
	v_mfma_f32_32x32x16_bf16 v[112:127], v[230:233], v[128:131], 0
	v_add_f32_e32 v96, 0, v80
	v_add_f32_e32 v162, v81, v96
	v_mfma_f32_32x32x16_bf16 v[96:111], v[234:237], v[128:131], 0
	s_waitcnt lgkmcnt(0)
	ds_read_b128 v[230:233], v188 offset:57344
	ds_read_b128 v[234:237], v189 offset:12288
	v_add_f32_e32 v162, v82, v162
	v_add_f32_e32 v162, v83, v162
	v_add_f32_e32 v162, v64, v162
	v_mfma_f32_32x32x16_bf16 v[112:127], v[244:247], v[238:241], v[112:127]
	v_exp_f32_e32 v66, v66
	v_exp_f32_e32 v67, v67
	v_add_f32_e32 v162, v65, v162
	v_mfma_f32_32x32x16_bf16 v[96:111], v[248:251], v[238:241], v[96:111]
	s_waitcnt lgkmcnt(0)
	ds_read_b128 v[244:247], v188 offset:57600
	ds_read_b128 v[248:251], v189 offset:12544
	ds_read_b128 v[238:241], v215 offset:1024
	v_add_f32_e32 v162, v84, v162
	v_add_f32_e32 v162, v85, v162
	v_add_f32_e32 v162, v66, v162
	v_mfma_f32_32x32x16_bf16 v[112:127], v[230:233], v[132:135], v[112:127]
	v_exp_f32_e32 v68, v68
	v_exp_f32_e32 v69, v69
	v_add_f32_e32 v162, v67, v162
	v_mfma_f32_32x32x16_bf16 v[96:111], v[234:237], v[132:135], v[96:111]
	s_waitcnt lgkmcnt(0)
; #define LAS __attribute__((address_space(3)))
; template <int S> __device__ __forceinline__ void fsm_chunk(f32x16& c0, f32x16& c1, float& ps, bf16x8& pa0, bf16x8& pa1, bf16x8& pa2, bf16x8& pa3) {
;   if constexpr (S < 8) { c1[2 * S] = __builtin_amdgcn_exp2f(c1[2 * S]); c1[2 * S + 1] = __builtin_amdgcn_exp2f(c1[2 * S + 1]); ps += c0[2 * S]; ps += c0[2 * S + 1]; if constexpr (S > 0) { ps += c1[2 * S - 2]; ps += c1[2 * S - 1]; } asm volatile("" : "+v"(c1), "+v"(ps)); }
;   else if constexpr (S == 8) { ps += c1[14]; ps += c1[15]; PK4(c0, 0, pa0); asm volatile("" : "+v"(pa0), "+v"(ps)); }
;   else if constexpr (S == 9) { PK4(c0, 8, pa1); asm volatile("" : "+v"(pa1)); }
;   else if constexpr (S == 10) { PK4(c1, 0, pa2); asm volatile("" : "+v"(pa2)); }
;   else { PK4(c1, 8, pa3); asm volatile("" : "+v"(pa3)); }
; }
; __device__ __forceinline__ void qk_fsm(f32x16& n0, f32x16& n1, f32x16& c0, f32x16& c1, float alC, float& l_reg, bf16x8& pa0, bf16x8& pa1, bf16x8& pa2, bf16x8& pa3,
;                                        const LAS char* kl, const int (&kx)[4], const bf16x8* qr, const LAS char* qrl) {
;   float ps = 0.f;
;     ...
;   QSLOT(0) QSLOT(1) QSLOT(2) QSLOT(3) QSLOT(4) QSLOT(5) QSLOT(6) QSLOT(7) QSLOT(8) QSLOT(9) QSLOT(10) QSLOT(11)
;     ...
;   { auto rr = __builtin_amdgcn_permlane32_swap(__float_as_uint(ps), __float_as_uint(ps), false, false); ps = __uint_as_float(rr[0]) + __uint_as_float(rr[1]); }
;   l_reg = l_reg * alC + ps;
; }
; __device__ __forceinline__ float fma_s(float a, float b, float c) { float d; asm volatile("v_fma_f32 %0, %1, %2, %3" : "=v"(d) : "v"(a), "v"(b), "v"(c)); return d; }
; template <int S> __device__ __forceinline__ void psm_chunk(f32x16& p0, f32x16& p1, float& mx, float& m_reg, float& alpha, float& mnC) {
;   constexpr float C = SCALE * 1.4426950408889634f; const float Cv = C;
;   if constexpr (S == 0) { mx = p0[0];
; #pragma unroll
;     for (int r = 1; r < 16; ++r) mx = fmaxf(mx, p0[r]); }
;   else if constexpr (S == 1) {
; #pragma unroll
;     for (int r = 0; r < 16; ++r) mx = fmaxf(mx, p1[r]);
;     { auto rr = __builtin_amdgcn_permlane32_swap(__float_as_uint(mx), __float_as_uint(mx), false, false); mx = fmaxf(__uint_as_float(rr[0]), __uint_as_float(rr[1])); }
;     const float mn = (mx - m_reg > THR / SCALE) ? fmaxf(m_reg, mx) : m_reg; alpha = __builtin_amdgcn_exp2f((m_reg - mn) * C); m_reg = mn; mnC = -mn * C; }
	ds_read_b128 v[230:233], v190 offset:57344
	ds_read_b128 v[234:237], v191 offset:12288
	v_add_f32_e32 v162, v86, v162
	v_add_f32_e32 v162, v87, v162
	v_add_f32_e32 v162, v68, v162
	v_mfma_f32_32x32x16_bf16 v[112:127], v[244:247], v[238:241], v[112:127]
	v_exp_f32_e32 v70, v70
	v_exp_f32_e32 v71, v71
	v_add_f32_e32 v162, v69, v162
	v_mfma_f32_32x32x16_bf16 v[96:111], v[248:251], v[238:241], v[96:111]
	s_waitcnt lgkmcnt(0)
	ds_read_b128 v[244:247], v190 offset:57600
	ds_read_b128 v[248:251], v191 offset:12544
	ds_read_b128 v[238:241], v215 offset:2048
	v_add_f32_e32 v162, v88, v162
	v_add_f32_e32 v162, v89, v162
	v_add_f32_e32 v162, v70, v162
	v_mfma_f32_32x32x16_bf16 v[112:127], v[230:233], v[136:139], v[112:127]
	v_exp_f32_e32 v72, v72
	v_exp_f32_e32 v73, v73
	v_add_f32_e32 v162, v71, v162
	v_mfma_f32_32x32x16_bf16 v[96:111], v[234:237], v[136:139], v[96:111]
	s_waitcnt lgkmcnt(0)
	ds_read_b128 v[230:233], v192 offset:57344
	ds_read_b128 v[234:237], v193 offset:12288
	v_add_f32_e32 v162, v90, v162
	v_add_f32_e32 v162, v91, v162
	v_add_f32_e32 v162, v72, v162
	v_mfma_f32_32x32x16_bf16 v[112:127], v[244:247], v[238:241], v[112:127]
	v_exp_f32_e32 v74, v74
	v_exp_f32_e32 v75, v75
	v_add_f32_e32 v162, v73, v162
	v_mfma_f32_32x32x16_bf16 v[96:111], v[248:251], v[238:241], v[96:111]
	s_waitcnt lgkmcnt(0)
	ds_read_b128 v[244:247], v192 offset:57600
	ds_read_b128 v[248:251], v193 offset:12544
	ds_read_b128 v[238:241], v215 offset:3072
	v_add_f32_e32 v162, v92, v162
	v_add_f32_e32 v162, v93, v162
	v_add_f32_e32 v162, v74, v162
	v_mfma_f32_32x32x16_bf16 v[112:127], v[230:233], v[156:159], v[112:127]
	v_exp_f32_e32 v76, v76
	v_exp_f32_e32 v77, v77
	v_add_f32_e32 v162, v75, v162
	v_mfma_f32_32x32x16_bf16 v[96:111], v[234:237], v[156:159], v[96:111]
	s_waitcnt lgkmcnt(0)
	ds_read_b128 v[230:233], v186 offset:57472
	ds_read_b128 v[234:237], v187 offset:12416
	v_add_f32_e32 v162, v94, v162
	v_add_f32_e32 v162, v95, v162
	v_add_f32_e32 v162, v76, v162
	v_mfma_f32_32x32x16_bf16 v[112:127], v[244:247], v[238:241], v[112:127]
	v_exp_f32_e32 v78, v78
	v_exp_f32_e32 v79, v79
	v_add_f32_e32 v162, v77, v162
	v_mfma_f32_32x32x16_bf16 v[96:111], v[248:251], v[238:241], v[96:111]
	s_waitcnt lgkmcnt(0)
	ds_read_b128 v[244:247], v188 offset:57472
	ds_read_b128 v[248:251], v189 offset:12416
	v_add_f32_e32 v162, v162, v78
	v_cvt_pk_bf16_f32 v80, v80, v81
	v_cvt_pk_bf16_f32 v81, v82, v83
	v_cvt_pk_bf16_f32 v82, v84, v85
	v_mfma_f32_32x32x16_bf16 v[112:127], v[230:233], v[152:155], v[112:127]
	v_cvt_pk_bf16_f32 v83, v86, v87
	v_add_f32_e32 v227, v79, v162
	v_permlane32_swap_b32_e32 v80, v82
	v_permlane32_swap_b32_e32 v81, v83
	v_mfma_f32_32x32x16_bf16 v[96:111], v[234:237], v[152:155], v[96:111]
	s_waitcnt lgkmcnt(0)
	ds_read_b128 v[230:233], v190 offset:57472
	ds_read_b128 v[234:237], v191 offset:12416
	v_cvt_pk_bf16_f32 v84, v88, v89
	v_cvt_pk_bf16_f32 v85, v90, v91
	v_cvt_pk_bf16_f32 v86, v92, v93
	v_mfma_f32_32x32x16_bf16 v[112:127], v[244:247], v[148:151], v[112:127]
	v_cvt_pk_bf16_f32 v87, v94, v95
	v_permlane32_swap_b32_e32 v84, v86
	v_mfma_f32_32x32x16_bf16 v[96:111], v[248:251], v[148:151], v[96:111]
	v_permlane32_swap_b32_e32 v85, v87
	s_waitcnt lgkmcnt(0)
	ds_read_b128 v[244:247], v192 offset:57472
	ds_read_b128 v[248:251], v193 offset:12416
	v_cvt_pk_bf16_f32 v64, v64, v65
	v_cvt_pk_bf16_f32 v65, v66, v67
	v_cvt_pk_bf16_f32 v66, v68, v69
	v_mfma_f32_32x32x16_bf16 v[112:127], v[230:233], v[144:147], v[112:127]
	v_cvt_pk_bf16_f32 v67, v70, v71
	v_permlane32_swap_b32_e32 v64, v66
	v_mfma_f32_32x32x16_bf16 v[96:111], v[234:237], v[144:147], v[96:111]
	v_permlane32_swap_b32_e32 v65, v67
	s_waitcnt lgkmcnt(0)
	ds_read_b64_tr_b16 v[234:235], v184
	ds_read_b64_tr_b16 v[236:237], v184 offset:2048
	ds_read_b64_tr_b16 v[238:239], v184 offset:4096
	ds_read_b64_tr_b16 v[240:241], v184 offset:6144
	v_cvt_pk_bf16_f32 v68, v72, v73
	v_cvt_pk_bf16_f32 v69, v74, v75
	v_cvt_pk_bf16_f32 v70, v76, v77
	v_mfma_f32_32x32x16_bf16 v[112:127], v[244:247], v[140:143], v[112:127]
	v_cvt_pk_bf16_f32 v71, v78, v79
	v_permlane32_swap_b32_e32 v68, v70
	v_mfma_f32_32x32x16_bf16 v[96:111], v[248:251], v[140:143], v[96:111]
	v_permlane32_swap_b32_e32 v69, v71
	v_mov_b32_e32 v229, v227
	s_nop 1
	v_permlane32_swap_b32_e32 v227, v229
	s_waitcnt lgkmcnt(0)
	ds_read_b64_tr_b16 v[72:73], v184 offset:8192
	ds_read_b64_tr_b16 v[74:75], v184 offset:10240
	ds_read_b64_tr_b16 v[76:77], v184 offset:12288
	ds_read_b64_tr_b16 v[78:79], v184 offset:14336
	v_max_f32_e32 v88, v113, v113
	v_max_f32_e32 v89, v112, v112
	v_mfma_f32_32x32x16_bf16 v[0:15], v[80:83], v[234:237], v[0:15]
	v_max_f32_e32 v88, v89, v88
	v_max3_f32 v88, v88, v114, v115
	v_max3_f32 v88, v88, v116, v117
	v_max3_f32 v252, v88, v118, v119
	v_max3_f32 v252, v252, v120, v121
	v_max3_f32 v252, v252, v122, v123
	v_max3_f32 v252, v252, v124, v125
	v_mfma_f32_32x32x16_bf16 v[0:15], v[84:87], v[238:241], v[0:15]
	v_max3_f32 v88, v252, v126, v127
	s_waitcnt lgkmcnt(0)
	ds_read_b64_tr_b16 v[234:235], v184 offset:512
	ds_read_b64_tr_b16 v[236:237], v184 offset:2560
	ds_read_b64_tr_b16 v[238:239], v184 offset:4608
	ds_read_b64_tr_b16 v[240:241], v184 offset:6656
	v_max3_f32 v88, v88, v96, v97
	v_max3_f32 v88, v88, v98, v99
	v_max3_f32 v88, v88, v100, v101
	v_max3_f32 v88, v88, v102, v103
	v_mfma_f32_32x32x16_bf16 v[0:15], v[64:67], v[72:75], v[0:15]
	v_max3_f32 v88, v88, v104, v105
	v_max3_f32 v88, v88, v106, v107
	v_max3_f32 v88, v88, v108, v109
	v_max3_f32 v88, v88, v110, v111
	v_mov_b32_e32 v89, v88
	s_nop 1
	v_permlane32_swap_b32_e32 v88, v89
	v_max_f32_e32 v89, v89, v89
	v_max_f32_e32 v88, v88, v88
	v_max_f32_e32 v88, v88, v89
	v_mfma_f32_32x32x16_bf16 v[0:15], v[68:71], v[76:79], v[0:15]
	v_sub_f32_e32 v89, v88, v228
	v_cmp_lt_f32_e32 vcc, s29, v89
	v_max_f32_e32 v89, v228, v228
	v_max_f32_e32 v89, v89, v88
	v_cndmask_b32_e32 v230, v228, v89, vcc
	v_sub_f32_e32 v89, v228, v230
	v_mul_f32_e32 v89, 0x3dd53b94, v89
	v_exp_f32_e32 v223, v89
	v_mul_f32_e32 v89, 0xbdd53b94, v230
	s_waitcnt lgkmcnt(0)
; #define LAS __attribute__((address_space(3)))
; __device__ __forceinline__ float fma_s(float a, float b, float c) { float d; asm volatile("v_fma_f32 %0, %1, %2, %3" : "=v"(d) : "v"(a), "v"(b), "v"(c)); return d; }
; template <int S> __device__ __forceinline__ void psm_chunk(f32x16& p0, f32x16& p1, float& mx, float& m_reg, float& alpha, float& mnC) {
;     ...
;   else if constexpr (S == 2) {
; #pragma unroll
;     for (int r = 0; r < 8; ++r) p0[r] = fma_s(p0[r], Cv, mnC); }
;   else if constexpr (S == 3) {
; #pragma unroll
;     for (int r = 8; r < 16; ++r) p0[r] = fma_s(p0[r], Cv, mnC);
; #pragma unroll
;     for (int r = 0; r < 4; ++r) p0[r] = __builtin_amdgcn_exp2f(p0[r]); }
;   else if constexpr (S == 4) {
; #pragma unroll
;     for (int r = 0; r < 8; ++r) p1[r] = fma_s(p1[r], Cv, mnC);
; #pragma unroll
;     for (int r = 4; r < 8; ++r) p0[r] = __builtin_amdgcn_exp2f(p0[r]); }
;   else if constexpr (S == 5) {
; #pragma unroll
;     for (int r = 8; r < 16; ++r) p1[r] = fma_s(p1[r], Cv, mnC);
; #pragma unroll
;     for (int r = 8; r < 12; ++r) p0[r] = __builtin_amdgcn_exp2f(p0[r]); }
;   else if constexpr (S == 6) {
; #pragma unroll
;     for (int r = 12; r < 16; ++r) p0[r] = __builtin_amdgcn_exp2f(p0[r]); }
;   if constexpr (S == 0 || S == 1) asm volatile("" : "+v"(mx), "+v"(alpha), "+v"(mnC), "+v"(m_reg));
;   else if constexpr (S < 7) asm volatile("" : "+v"(p0), "+v"(p1));
; }
; __device__ __forceinline__ void pv_psm(f32x16* o, const LAS char* vl, bf16x8 pa0, bf16x8 pa1, bf16x8 pa2, bf16x8 pa3, f32x16& n0, f32x16& n1, float& m_reg, float& alN) {
;   float mx = 0.f, mnC = 0.f;
;     ...
;   VSLOT(0) VSLOT(1) VSLOT(2) VSLOT(3) VSLOT(4) VSLOT(5) VSLOT(6) VSLOT(7)
	ds_read_b64_tr_b16 v[72:73], v184 offset:8704
	ds_read_b64_tr_b16 v[74:75], v184 offset:10752
	ds_read_b64_tr_b16 v[76:77], v184 offset:12800
	ds_read_b64_tr_b16 v[78:79], v184 offset:14848
	v_fma_f32 v112, v112, v211, v89
	v_fma_f32 v113, v113, v211, v89
	v_mfma_f32_32x32x16_bf16 v[48:63], v[80:83], v[234:237], v[48:63]
	v_fma_f32 v114, v114, v211, v89
	v_fma_f32 v115, v115, v211, v89
	v_fma_f32 v116, v116, v211, v89
	v_fma_f32 v117, v117, v211, v89
	v_fma_f32 v118, v118, v211, v89
	v_fma_f32 v119, v119, v211, v89
	v_mfma_f32_32x32x16_bf16 v[48:63], v[84:87], v[238:241], v[48:63]
	s_waitcnt lgkmcnt(0)
	ds_read_b64_tr_b16 v[234:235], v184 offset:1024
	ds_read_b64_tr_b16 v[236:237], v184 offset:3072
	ds_read_b64_tr_b16 v[238:239], v184 offset:5120
	ds_read_b64_tr_b16 v[240:241], v184 offset:7168
	v_fma_f32 v120, v120, v211, v89
	v_fma_f32 v121, v121, v211, v89
	v_mfma_f32_32x32x16_bf16 v[48:63], v[64:67], v[72:75], v[48:63]
	v_fma_f32 v122, v122, v211, v89
	v_fma_f32 v123, v123, v211, v89
	v_fma_f32 v124, v124, v211, v89
	v_exp_f32_e32 v112, v112
	v_exp_f32_e32 v113, v113
	v_exp_f32_e32 v114, v114
	v_exp_f32_e32 v115, v115
	v_mfma_f32_32x32x16_bf16 v[48:63], v[68:71], v[76:79], v[48:63]
	v_fma_f32 v125, v125, v211, v89
	v_fma_f32 v126, v126, v211, v89
	v_fma_f32 v127, v127, v211, v89
	s_nop 0
	s_waitcnt lgkmcnt(0)
	ds_read_b64_tr_b16 v[72:73], v184 offset:9216
	ds_read_b64_tr_b16 v[74:75], v184 offset:11264
	ds_read_b64_tr_b16 v[76:77], v184 offset:13312
	ds_read_b64_tr_b16 v[78:79], v184 offset:15360
	v_fma_f32 v96, v96, v211, v89
	v_fma_f32 v97, v97, v211, v89
	v_mfma_f32_32x32x16_bf16 v[32:47], v[80:83], v[234:237], v[32:47]
	v_fma_f32 v98, v98, v211, v89
	v_fma_f32 v99, v99, v211, v89
	v_fma_f32 v100, v100, v211, v89
	v_exp_f32_e32 v116, v116
	v_exp_f32_e32 v117, v117
	v_exp_f32_e32 v118, v118
	v_exp_f32_e32 v119, v119
	v_mfma_f32_32x32x16_bf16 v[32:47], v[84:87], v[238:241], v[32:47]
	v_fma_f32 v101, v101, v211, v89
	v_fma_f32 v102, v102, v211, v89
	v_fma_f32 v103, v103, v211, v89
	s_nop 0
	s_waitcnt lgkmcnt(0)
	ds_read_b64_tr_b16 v[234:235], v184 offset:1536
	ds_read_b64_tr_b16 v[236:237], v184 offset:3584
	ds_read_b64_tr_b16 v[238:239], v184 offset:5632
	ds_read_b64_tr_b16 v[240:241], v184 offset:7680
	v_fma_f32 v104, v104, v211, v89
	v_fma_f32 v105, v105, v211, v89
	v_mfma_f32_32x32x16_bf16 v[32:47], v[64:67], v[72:75], v[32:47]
	v_fma_f32 v106, v106, v211, v89
	v_fma_f32 v107, v107, v211, v89
	v_fma_f32 v108, v108, v211, v89
	v_exp_f32_e32 v120, v120
	v_exp_f32_e32 v121, v121
	v_exp_f32_e32 v122, v122
	v_exp_f32_e32 v123, v123
	v_mfma_f32_32x32x16_bf16 v[32:47], v[68:71], v[76:79], v[32:47]
	v_fma_f32 v109, v109, v211, v89
	v_fma_f32 v110, v110, v211, v89
	v_fma_f32 v111, v111, v211, v89
	s_nop 0
	s_waitcnt lgkmcnt(0)
	ds_read_b64_tr_b16 v[72:73], v184 offset:9728
	ds_read_b64_tr_b16 v[74:75], v184 offset:11776
	ds_read_b64_tr_b16 v[76:77], v184 offset:13824
	ds_read_b64_tr_b16 v[78:79], v184 offset:15872
	v_exp_f32_e32 v124, v124
	v_exp_f32_e32 v125, v125
	v_mfma_f32_32x32x16_bf16 v[16:31], v[80:83], v[234:237], v[16:31]
	v_exp_f32_e32 v126, v126
	v_exp_f32_e32 v127, v127
	v_mfma_f32_32x32x16_bf16 v[16:31], v[84:87], v[238:241], v[16:31]
	s_waitcnt lgkmcnt(0)
	v_mfma_f32_32x32x16_bf16 v[16:31], v[64:67], v[72:75], v[16:31]
	v_mfma_f32_32x32x16_bf16 v[16:31], v[68:71], v[76:79], v[16:31]
	s_waitcnt vmcnt(0) lgkmcnt(0)
	s_barrier
	v_cmp_gt_f32_e32 vcc, 1.0, v223
	s_cbranch_vccz .LBB0_1015
	s_and_saveexec_b64 s[6:7], s[40:41]
	ds_write_b32 v185, v223 offset:128
	s_or_b64 exec, exec, s[6:7]
	s_waitcnt lgkmcnt(0)
	ds_read_b128 v[64:67], v196 offset:224
	ds_read_b128 v[68:71], v196 offset:192
	ds_read_b128 v[72:75], v196 offset:160
	ds_read_b128 v[76:79], v196 offset:128
	s_waitcnt lgkmcnt(0)
	v_pk_mul_f32 v[12:13], v[12:13], v[64:65]
	v_pk_mul_f32 v[8:9], v[8:9], v[68:69]
	v_pk_mul_f32 v[4:5], v[4:5], v[72:73]
	v_pk_mul_f32 v[14:15], v[14:15], v[66:67]
	v_pk_mul_f32 v[10:11], v[10:11], v[70:71]
	v_pk_mul_f32 v[6:7], v[6:7], v[74:75]
	v_pk_mul_f32 v[2:3], v[2:3], v[78:79]
	v_pk_mul_f32 v[0:1], v[0:1], v[76:77]
	v_pk_mul_f32 v[60:61], v[60:61], v[64:65]
	v_pk_mul_f32 v[56:57], v[56:57], v[68:69]
	v_pk_mul_f32 v[52:53], v[52:53], v[72:73]
	v_pk_mul_f32 v[62:63], v[62:63], v[66:67]
	v_pk_mul_f32 v[58:59], v[58:59], v[70:71]
	v_pk_mul_f32 v[54:55], v[54:55], v[74:75]
	v_pk_mul_f32 v[50:51], v[50:51], v[78:79]
	v_pk_mul_f32 v[48:49], v[48:49], v[76:77]
	v_pk_mul_f32 v[44:45], v[44:45], v[64:65]
	v_pk_mul_f32 v[40:41], v[40:41], v[68:69]
	v_pk_mul_f32 v[36:37], v[36:37], v[72:73]
	v_pk_mul_f32 v[46:47], v[46:47], v[66:67]
	v_pk_mul_f32 v[42:43], v[42:43], v[70:71]
	v_pk_mul_f32 v[38:39], v[38:39], v[74:75]
	v_pk_mul_f32 v[34:35], v[34:35], v[78:79]
	v_pk_mul_f32 v[32:33], v[32:33], v[76:77]
	v_pk_mul_f32 v[28:29], v[28:29], v[64:65]
	v_pk_mul_f32 v[24:25], v[24:25], v[68:69]
	v_pk_mul_f32 v[20:21], v[20:21], v[72:73]
	v_pk_mul_f32 v[30:31], v[30:31], v[66:67]
	v_pk_mul_f32 v[26:27], v[26:27], v[70:71]
	v_pk_mul_f32 v[22:23], v[22:23], v[74:75]
	v_pk_mul_f32 v[18:19], v[18:19], v[78:79]
	v_pk_mul_f32 v[16:17], v[16:17], v[76:77]
; #define LAS __attribute__((address_space(3)))
; __device__ __forceinline__ void qk_fsm(f32x16& n0, f32x16& n1, f32x16& c0, f32x16& c1, float alC, float& l_reg, bf16x8& pa0, bf16x8& pa1, bf16x8& pa2, bf16x8& pa3,
;                                        const LAS char* kl, const int (&kx)[4], const bf16x8* qr, const LAS char* qrl) {
;   float ps = 0.f;
;     ...
;   QSLOT(0) QSLOT(1) QSLOT(2) QSLOT(3) QSLOT(4) QSLOT(5) QSLOT(6) QSLOT(7) QSLOT(8) QSLOT(9) QSLOT(10) QSLOT(11)
; __device__ __forceinline__ void attn_unit(const bf16_t* __restrict__ Qb, const bf16_t* __restrict__ Kh, const bf16_t* __restrict__ Vh, bf16_t* __restrict__ Ob, float* __restrict__ ssq, char* lds, LAS unsigned char* ldsl, ...
;     ...
;   for (int j = 0; j < NT - 2; j += 2) {
;     STEP(pA0, pA1, alA, pB0, pB1, mnB, alB, j, true, true);
;     STEP(pB0, pB1, alB, pA0, pA1, mnA, alA, j + 1, true, true);
.LBB0_1015:
	ds_read_b128 v[232:235], v186 offset:32768
	ds_read_b128 v[236:239], v186 offset:45056
	s_add_u32 s4, s12, s31
	s_addc_u32 s5, s13, s9
	s_add_u32 s4, s4, 0x1dd12000
	s_addc_u32 s5, s5, 0
	s_add_u32 s6, s12, s90
	s_addc_u32 s7, s13, s91
	s_add_u32 s6, s6, 0x25508000
	s_addc_u32 s7, s7, 0
	s_add_i32 m0, s98, 0xe000
	s_nop 0
	global_load_lds_dwordx4 v177, s[4:5]
	s_add_i32 m0, s98, 0x10000
	s_nop 0
	global_load_lds_dwordx4 v178, s[4:5]
	s_add_i32 m0, s98, 0x12000
	s_nop 0
	global_load_lds_dwordx4 v179, s[4:5]
	s_mov_b32 m0, s98
	s_nop 0
	global_load_lds_dwordx4 v180, s[6:7]
	s_add_i32 m0, s98, 0x2000
	s_nop 0
	global_load_lds_dwordx4 v181, s[6:7]
	s_waitcnt lgkmcnt(0)
	ds_read_b128 v[244:247], v186 offset:33024
	ds_read_b128 v[248:251], v186 offset:45312
	ds_read_b128 v[240:243], v215
	v_exp_f32_e32 v96, v96
	v_exp_f32_e32 v97, v97
	v_mfma_f32_32x32x16_bf16 v[80:95], v[232:235], v[128:131], 0
	v_add_f32_e32 v64, 0, v112
	v_add_f32_e32 v162, v113, v64
	v_mfma_f32_32x32x16_bf16 v[64:79], v[236:239], v[128:131], 0
	s_waitcnt lgkmcnt(0)
	ds_read_b128 v[232:235], v188 offset:32768
	ds_read_b128 v[236:239], v188 offset:45056
	v_add_f32_e32 v162, v114, v162
	v_add_f32_e32 v162, v115, v162
	v_add_f32_e32 v162, v96, v162
	v_mfma_f32_32x32x16_bf16 v[80:95], v[244:247], v[240:243], v[80:95]
	v_exp_f32_e32 v98, v98
	v_exp_f32_e32 v99, v99
	v_add_f32_e32 v162, v97, v162
	v_mfma_f32_32x32x16_bf16 v[64:79], v[248:251], v[240:243], v[64:79]
	s_waitcnt lgkmcnt(0)
	ds_read_b128 v[244:247], v188 offset:33024
	ds_read_b128 v[248:251], v188 offset:45312
	ds_read_b128 v[240:243], v215 offset:1024
	v_add_f32_e32 v162, v116, v162
	v_add_f32_e32 v162, v117, v162
	v_add_f32_e32 v162, v98, v162
	v_mfma_f32_32x32x16_bf16 v[80:95], v[232:235], v[132:135], v[80:95]
	v_exp_f32_e32 v100, v100
	v_exp_f32_e32 v101, v101
	v_add_f32_e32 v162, v99, v162
	v_mfma_f32_32x32x16_bf16 v[64:79], v[236:239], v[132:135], v[64:79]
	s_waitcnt lgkmcnt(0)
	ds_read_b128 v[232:235], v190 offset:32768
	ds_read_b128 v[236:239], v190 offset:45056
	v_add_f32_e32 v162, v118, v162
	v_add_f32_e32 v162, v119, v162
	v_add_f32_e32 v162, v100, v162
	v_mfma_f32_32x32x16_bf16 v[80:95], v[244:247], v[240:243], v[80:95]
	v_exp_f32_e32 v102, v102
	v_exp_f32_e32 v103, v103
	v_add_f32_e32 v162, v101, v162
	v_mfma_f32_32x32x16_bf16 v[64:79], v[248:251], v[240:243], v[64:79]
	s_waitcnt lgkmcnt(0)
	ds_read_b128 v[244:247], v190 offset:33024
	ds_read_b128 v[248:251], v190 offset:45312
	ds_read_b128 v[240:243], v215 offset:2048
	v_add_f32_e32 v162, v120, v162
	v_add_f32_e32 v162, v121, v162
	v_add_f32_e32 v162, v102, v162
	v_mfma_f32_32x32x16_bf16 v[80:95], v[232:235], v[136:139], v[80:95]
	v_exp_f32_e32 v104, v104
	v_exp_f32_e32 v105, v105
	v_add_f32_e32 v162, v103, v162
	v_mfma_f32_32x32x16_bf16 v[64:79], v[236:239], v[136:139], v[64:79]
	s_waitcnt lgkmcnt(0)
	ds_read_b128 v[232:235], v192 offset:32768
	ds_read_b128 v[236:239], v192 offset:45056
	v_add_f32_e32 v162, v122, v162
	v_add_f32_e32 v162, v123, v162
	v_add_f32_e32 v162, v104, v162
	v_mfma_f32_32x32x16_bf16 v[80:95], v[244:247], v[240:243], v[80:95]
	v_exp_f32_e32 v106, v106
	v_exp_f32_e32 v107, v107
	v_add_f32_e32 v162, v105, v162
	v_mfma_f32_32x32x16_bf16 v[64:79], v[248:251], v[240:243], v[64:79]
	s_waitcnt lgkmcnt(0)
	ds_read_b128 v[244:247], v192 offset:33024
	ds_read_b128 v[248:251], v192 offset:45312
	ds_read_b128 v[240:243], v215 offset:3072
	v_add_f32_e32 v162, v124, v162
	v_add_f32_e32 v162, v125, v162
	v_add_f32_e32 v162, v106, v162
	v_mfma_f32_32x32x16_bf16 v[80:95], v[232:235], v[156:159], v[80:95]
	v_exp_f32_e32 v108, v108
	v_exp_f32_e32 v109, v109
	v_add_f32_e32 v162, v107, v162
	v_mfma_f32_32x32x16_bf16 v[64:79], v[236:239], v[156:159], v[64:79]
	s_waitcnt lgkmcnt(0)
	ds_read_b128 v[232:235], v186 offset:32896
	ds_read_b128 v[236:239], v186 offset:45184
	v_add_f32_e32 v162, v126, v162
	v_add_f32_e32 v162, v127, v162
	v_add_f32_e32 v162, v108, v162
	v_mfma_f32_32x32x16_bf16 v[80:95], v[244:247], v[240:243], v[80:95]
	v_exp_f32_e32 v110, v110
	v_exp_f32_e32 v111, v111
	v_add_f32_e32 v162, v109, v162
	v_mfma_f32_32x32x16_bf16 v[64:79], v[248:251], v[240:243], v[64:79]
	s_waitcnt lgkmcnt(0)
	ds_read_b128 v[244:247], v188 offset:32896
	ds_read_b128 v[248:251], v188 offset:45184
	v_add_f32_e32 v162, v162, v110
	v_cvt_pk_bf16_f32 v112, v112, v113
	v_cvt_pk_bf16_f32 v113, v114, v115
	v_cvt_pk_bf16_f32 v114, v116, v117
	v_mfma_f32_32x32x16_bf16 v[80:95], v[232:235], v[152:155], v[80:95]
	v_cvt_pk_bf16_f32 v115, v118, v119
	v_add_f32_e32 v231, v111, v162
	v_permlane32_swap_b32_e32 v112, v114
	v_permlane32_swap_b32_e32 v113, v115
	v_mfma_f32_32x32x16_bf16 v[64:79], v[236:239], v[152:155], v[64:79]
	s_waitcnt lgkmcnt(0)
	ds_read_b128 v[232:235], v190 offset:32896
	ds_read_b128 v[236:239], v190 offset:45184
	v_cvt_pk_bf16_f32 v116, v120, v121
	v_cvt_pk_bf16_f32 v117, v122, v123
	v_cvt_pk_bf16_f32 v118, v124, v125
	v_mfma_f32_32x32x16_bf16 v[80:95], v[244:247], v[148:151], v[80:95]
	v_cvt_pk_bf16_f32 v119, v126, v127
	v_permlane32_swap_b32_e32 v116, v118
	v_mfma_f32_32x32x16_bf16 v[64:79], v[248:251], v[148:151], v[64:79]
	v_permlane32_swap_b32_e32 v117, v119
	s_waitcnt lgkmcnt(0)
	ds_read_b128 v[244:247], v192 offset:32896
	ds_read_b128 v[248:251], v192 offset:45184
	v_cvt_pk_bf16_f32 v96, v96, v97
	v_cvt_pk_bf16_f32 v97, v98, v99
	v_cvt_pk_bf16_f32 v98, v100, v101
	v_mfma_f32_32x32x16_bf16 v[80:95], v[232:235], v[144:147], v[80:95]
	v_cvt_pk_bf16_f32 v99, v102, v103
	v_permlane32_swap_b32_e32 v96, v98
	v_mfma_f32_32x32x16_bf16 v[64:79], v[236:239], v[144:147], v[64:79]
	v_permlane32_swap_b32_e32 v97, v99
	s_waitcnt lgkmcnt(0)
; #define LAS __attribute__((address_space(3)))
; __device__ __forceinline__ float fma_s(float a, float b, float c) { float d; asm volatile("v_fma_f32 %0, %1, %2, %3" : "=v"(d) : "v"(a), "v"(b), "v"(c)); return d; }
; template <int S> __device__ __forceinline__ void psm_chunk(f32x16& p0, f32x16& p1, float& mx, float& m_reg, float& alpha, float& mnC) {
;   constexpr float C = SCALE * 1.4426950408889634f; const float Cv = C;
;   if constexpr (S == 0) { mx = p0[0];
; #pragma unroll
;     for (int r = 1; r < 16; ++r) mx = fmaxf(mx, p0[r]); }
;   else if constexpr (S == 1) {
; #pragma unroll
;     for (int r = 0; r < 16; ++r) mx = fmaxf(mx, p1[r]);
;     { auto rr = __builtin_amdgcn_permlane32_swap(__float_as_uint(mx), __float_as_uint(mx), false, false); mx = fmaxf(__uint_as_float(rr[0]), __uint_as_float(rr[1])); }
;     const float mn = (mx - m_reg > THR / SCALE) ? fmaxf(m_reg, mx) : m_reg; alpha = __builtin_amdgcn_exp2f((m_reg - mn) * C); m_reg = mn; mnC = -mn * C; }
;   else if constexpr (S == 2) {
; #pragma unroll
;     for (int r = 0; r < 8; ++r) p0[r] = fma_s(p0[r], Cv, mnC); }
;   else if constexpr (S == 3) {
; #pragma unroll
;     for (int r = 8; r < 16; ++r) p0[r] = fma_s(p0[r], Cv, mnC);
; #pragma unroll
;     for (int r = 0; r < 4; ++r) p0[r] = __builtin_amdgcn_exp2f(p0[r]); }
;   else if constexpr (S == 4) {
; #pragma unroll
;     for (int r = 0; r < 8; ++r) p1[r] = fma_s(p1[r], Cv, mnC);
; #pragma unroll
;     for (int r = 4; r < 8; ++r) p0[r] = __builtin_amdgcn_exp2f(p0[r]); }
;   else if constexpr (S == 5) {
; #pragma unroll
;     for (int r = 8; r < 16; ++r) p1[r] = fma_s(p1[r], Cv, mnC);
; #pragma unroll
;     for (int r = 8; r < 12; ++r) p0[r] = __builtin_amdgcn_exp2f(p0[r]); }
;   else if constexpr (S == 6) {
; #pragma unroll
;     for (int r = 12; r < 16; ++r) p0[r] = __builtin_amdgcn_exp2f(p0[r]); }
;   if constexpr (S == 0 || S == 1) asm volatile("" : "+v"(mx), "+v"(alpha), "+v"(mnC), "+v"(m_reg));
;   else if constexpr (S < 7) asm volatile("" : "+v"(p0), "+v"(p1));
; }
; __device__ __forceinline__ void pv_psm(f32x16* o, const LAS char* vl, bf16x8 pa0, bf16x8 pa1, bf16x8 pa2, bf16x8 pa3, f32x16& n0, f32x16& n1, float& m_reg, float& alN) {
;   float mx = 0.f, mnC = 0.f;
;     ...
;   VSLOT(0) VSLOT(1) VSLOT(2) VSLOT(3) VSLOT(4) VSLOT(5) VSLOT(6) VSLOT(7)
	ds_read_b64_tr_b16 v[232:233], v184 offset:16384
	ds_read_b64_tr_b16 v[234:235], v184 offset:18432
	ds_read_b64_tr_b16 v[236:237], v184 offset:20480
	ds_read_b64_tr_b16 v[238:239], v184 offset:22528
	v_cvt_pk_bf16_f32 v100, v104, v105
	v_cvt_pk_bf16_f32 v101, v106, v107
	v_cvt_pk_bf16_f32 v102, v108, v109
	v_mfma_f32_32x32x16_bf16 v[80:95], v[244:247], v[140:143], v[80:95]
	v_cvt_pk_bf16_f32 v103, v110, v111
	v_permlane32_swap_b32_e32 v100, v102
	v_mfma_f32_32x32x16_bf16 v[64:79], v[248:251], v[140:143], v[64:79]
	v_permlane32_swap_b32_e32 v101, v103
	v_mov_b32_e32 v104, v231
	s_nop 1
	v_permlane32_swap_b32_e32 v231, v104
	s_waitcnt lgkmcnt(0)
	ds_read_b64_tr_b16 v[106:107], v184 offset:24576
	ds_read_b64_tr_b16 v[108:109], v184 offset:26624
	ds_read_b64_tr_b16 v[120:121], v184 offset:28672
	ds_read_b64_tr_b16 v[122:123], v184 offset:30720
	v_max_f32_e32 v105, v81, v81
	v_max_f32_e32 v110, v80, v80
	v_mfma_f32_32x32x16_bf16 v[0:15], v[112:115], v[232:235], v[0:15]
	v_max_f32_e32 v105, v110, v105
	v_max3_f32 v105, v105, v82, v83
	v_max3_f32 v105, v105, v84, v85
	v_max3_f32 v105, v105, v86, v87
	v_max3_f32 v105, v105, v88, v89
	v_max3_f32 v105, v105, v90, v91
	v_max3_f32 v105, v105, v92, v93
	v_mfma_f32_32x32x16_bf16 v[0:15], v[116:119], v[236:239], v[0:15]
	v_max3_f32 v105, v105, v94, v95
	s_waitcnt lgkmcnt(0)
	ds_read_b64_tr_b16 v[232:233], v184 offset:16896
	ds_read_b64_tr_b16 v[234:235], v184 offset:18944
	ds_read_b64_tr_b16 v[236:237], v184 offset:20992
	ds_read_b64_tr_b16 v[238:239], v184 offset:23040
	v_max3_f32 v105, v105, v64, v65
	v_max3_f32 v105, v105, v66, v67
	v_max3_f32 v105, v105, v68, v69
	v_max3_f32 v105, v105, v70, v71
	v_mfma_f32_32x32x16_bf16 v[0:15], v[96:99], v[106:109], v[0:15]
	v_max3_f32 v105, v105, v72, v73
	v_max3_f32 v105, v105, v74, v75
	v_max3_f32 v105, v105, v76, v77
	v_max3_f32 v105, v105, v78, v79
	v_mov_b32_e32 v110, v105
	s_nop 1
	v_permlane32_swap_b32_e32 v105, v110
	v_max_f32_e32 v110, v110, v110
	v_max_f32_e32 v105, v105, v105
	v_max_f32_e32 v105, v105, v110
	v_mfma_f32_32x32x16_bf16 v[0:15], v[100:103], v[120:123], v[0:15]
	v_sub_f32_e32 v110, v105, v230
	v_cmp_lt_f32_e32 vcc, s29, v110
	v_max_f32_e32 v110, v230, v230
	v_max_f32_e32 v110, v110, v105
	v_cndmask_b32_e32 v228, v230, v110, vcc
	v_sub_f32_e32 v110, v230, v228
	v_mul_f32_e32 v110, 0x3dd53b94, v110
	v_exp_f32_e32 v162, v110
	v_mul_f32_e32 v110, 0xbdd53b94, v228
	s_waitcnt lgkmcnt(0)
	ds_read_b64_tr_b16 v[106:107], v184 offset:25088
	ds_read_b64_tr_b16 v[108:109], v184 offset:27136
	ds_read_b64_tr_b16 v[120:121], v184 offset:29184
	ds_read_b64_tr_b16 v[122:123], v184 offset:31232
	v_fma_f32 v80, v80, v211, v110
	v_fma_f32 v81, v81, v211, v110
	v_mfma_f32_32x32x16_bf16 v[48:63], v[112:115], v[232:235], v[48:63]
	v_fma_f32 v82, v82, v211, v110
	v_fma_f32 v83, v83, v211, v110
	v_fma_f32 v84, v84, v211, v110
	v_fma_f32 v85, v85, v211, v110
	v_fma_f32 v86, v86, v211, v110
	v_fma_f32 v87, v87, v211, v110
	v_mfma_f32_32x32x16_bf16 v[48:63], v[116:119], v[236:239], v[48:63]
	s_waitcnt lgkmcnt(0)
	ds_read_b64_tr_b16 v[232:233], v184 offset:17408
	ds_read_b64_tr_b16 v[234:235], v184 offset:19456
	ds_read_b64_tr_b16 v[236:237], v184 offset:21504
	ds_read_b64_tr_b16 v[238:239], v184 offset:23552
	v_fma_f32 v88, v88, v211, v110
	v_fma_f32 v89, v89, v211, v110
	v_mfma_f32_32x32x16_bf16 v[48:63], v[96:99], v[106:109], v[48:63]
	v_fma_f32 v90, v90, v211, v110
	v_fma_f32 v91, v91, v211, v110
	v_fma_f32 v92, v92, v211, v110
	v_exp_f32_e32 v80, v80
	v_exp_f32_e32 v81, v81
	v_exp_f32_e32 v82, v82
	v_exp_f32_e32 v83, v83
	v_mfma_f32_32x32x16_bf16 v[48:63], v[100:103], v[120:123], v[48:63]
	v_fma_f32 v93, v93, v211, v110
	v_fma_f32 v94, v94, v211, v110
	v_fma_f32 v95, v95, v211, v110
	s_nop 0
	s_waitcnt lgkmcnt(0)
	ds_read_b64_tr_b16 v[106:107], v184 offset:25600
	ds_read_b64_tr_b16 v[108:109], v184 offset:27648
	ds_read_b64_tr_b16 v[120:121], v184 offset:29696
	ds_read_b64_tr_b16 v[122:123], v184 offset:31744
	v_fma_f32 v64, v64, v211, v110
	v_fma_f32 v65, v65, v211, v110
	v_mfma_f32_32x32x16_bf16 v[32:47], v[112:115], v[232:235], v[32:47]
	v_fma_f32 v66, v66, v211, v110
	v_fma_f32 v67, v67, v211, v110
	v_fma_f32 v68, v68, v211, v110
	v_exp_f32_e32 v84, v84
	v_exp_f32_e32 v85, v85
	v_exp_f32_e32 v86, v86
	v_exp_f32_e32 v87, v87
	v_mfma_f32_32x32x16_bf16 v[32:47], v[116:119], v[236:239], v[32:47]
	v_fma_f32 v69, v69, v211, v110
	v_fma_f32 v70, v70, v211, v110
	v_fma_f32 v71, v71, v211, v110
	s_nop 0
	s_waitcnt lgkmcnt(0)
	ds_read_b64_tr_b16 v[232:233], v184 offset:17920
	ds_read_b64_tr_b16 v[234:235], v184 offset:19968
	ds_read_b64_tr_b16 v[236:237], v184 offset:22016
	ds_read_b64_tr_b16 v[238:239], v184 offset:24064
	v_fma_f32 v72, v72, v211, v110
	v_fma_f32 v73, v73, v211, v110
	v_mfma_f32_32x32x16_bf16 v[32:47], v[96:99], v[106:109], v[32:47]
	v_fma_f32 v74, v74, v211, v110
	v_fma_f32 v75, v75, v211, v110
	v_fma_f32 v76, v76, v211, v110
	v_exp_f32_e32 v88, v88
	v_exp_f32_e32 v89, v89
	v_exp_f32_e32 v90, v90
	v_exp_f32_e32 v91, v91
	v_mfma_f32_32x32x16_bf16 v[32:47], v[100:103], v[120:123], v[32:47]
	v_fma_f32 v77, v77, v211, v110
	v_fma_f32 v78, v78, v211, v110
	v_fma_f32 v79, v79, v211, v110
	s_nop 0
	s_waitcnt lgkmcnt(0)
	ds_read_b64_tr_b16 v[106:107], v184 offset:26112
	ds_read_b64_tr_b16 v[108:109], v184 offset:28160
	ds_read_b64_tr_b16 v[120:121], v184 offset:30208
	ds_read_b64_tr_b16 v[122:123], v184 offset:32256
	v_exp_f32_e32 v92, v92
	v_exp_f32_e32 v93, v93
	v_mfma_f32_32x32x16_bf16 v[16:31], v[112:115], v[232:235], v[16:31]
	v_exp_f32_e32 v94, v94
	v_exp_f32_e32 v95, v95
	v_mfma_f32_32x32x16_bf16 v[16:31], v[116:119], v[236:239], v[16:31]
	s_waitcnt lgkmcnt(0)
	v_mfma_f32_32x32x16_bf16 v[16:31], v[96:99], v[106:109], v[16:31]
	v_mfma_f32_32x32x16_bf16 v[16:31], v[100:103], v[120:123], v[16:31]
	s_waitcnt vmcnt(0) lgkmcnt(0)
	s_barrier
	v_cmp_gt_f32_e32 vcc, 1.0, v162
	s_cbranch_vccz .LBB0_1019
	s_and_saveexec_b64 s[6:7], s[40:41]
	ds_write_b32 v185, v162 offset:128
	s_or_b64 exec, exec, s[6:7]
	s_waitcnt lgkmcnt(0)
	ds_read_b128 v[96:99], v196 offset:224
	ds_read_b128 v[100:103], v196 offset:192
	ds_read_b128 v[106:109], v196 offset:160
	ds_read_b128 v[110:113], v196 offset:128
	s_waitcnt lgkmcnt(0)
	v_pk_mul_f32 v[12:13], v[12:13], v[96:97]
	v_pk_mul_f32 v[8:9], v[8:9], v[100:101]
	v_pk_mul_f32 v[4:5], v[4:5], v[106:107]
	v_pk_mul_f32 v[14:15], v[14:15], v[98:99]
	v_pk_mul_f32 v[10:11], v[10:11], v[102:103]
	v_pk_mul_f32 v[6:7], v[6:7], v[108:109]
	v_pk_mul_f32 v[2:3], v[2:3], v[112:113]
	v_pk_mul_f32 v[0:1], v[0:1], v[110:111]
	v_pk_mul_f32 v[60:61], v[60:61], v[96:97]
	v_pk_mul_f32 v[56:57], v[56:57], v[100:101]
	v_pk_mul_f32 v[52:53], v[52:53], v[106:107]
	v_pk_mul_f32 v[62:63], v[62:63], v[98:99]
	v_pk_mul_f32 v[58:59], v[58:59], v[102:103]
	v_pk_mul_f32 v[54:55], v[54:55], v[108:109]
	v_pk_mul_f32 v[50:51], v[50:51], v[112:113]
	v_pk_mul_f32 v[48:49], v[48:49], v[110:111]
	v_pk_mul_f32 v[44:45], v[44:45], v[96:97]
	v_pk_mul_f32 v[40:41], v[40:41], v[100:101]
	v_pk_mul_f32 v[36:37], v[36:37], v[106:107]
	v_pk_mul_f32 v[46:47], v[46:47], v[98:99]
	v_pk_mul_f32 v[42:43], v[42:43], v[102:103]
	v_pk_mul_f32 v[38:39], v[38:39], v[108:109]
	v_pk_mul_f32 v[34:35], v[34:35], v[112:113]
	v_pk_mul_f32 v[32:33], v[32:33], v[110:111]
	v_pk_mul_f32 v[28:29], v[28:29], v[96:97]
	v_pk_mul_f32 v[24:25], v[24:25], v[100:101]
	v_pk_mul_f32 v[20:21], v[20:21], v[106:107]
	v_pk_mul_f32 v[30:31], v[30:31], v[98:99]
	v_pk_mul_f32 v[26:27], v[26:27], v[102:103]
	v_pk_mul_f32 v[22:23], v[22:23], v[108:109]
	v_pk_mul_f32 v[18:19], v[18:19], v[112:113]
	v_pk_mul_f32 v[16:17], v[16:17], v[110:111]

; #define LAS __attribute__((address_space(3)))
; __global__ void __launch_bounds__(512, 2) fwd_kernel(KP p) {
;     extern __shared__ __attribute__((aligned(16))) unsigned char lds_raw[];
;     LAS unsigned char* lds = (LAS unsigned char*)lds_raw;
;     const int wave = __builtin_amdgcn_readfirstlane((int)threadIdx.x >> 6);
;     const int G = gridDim.x, b = blockIdx.x;
;     const int gw = b * 8 + wave, NGW = G * 8;
;     const int gw2 = wave * G + b;
;     const int NGT = G * 512;
	.amdhsa_kernel _Z10fwd_kernel2KP
		.amdhsa_group_segment_fixed_size 0
		.amdhsa_private_segment_fixed_size 0
		.amdhsa_kernarg_size 512
		.amdhsa_user_sgpr_count 2
		.amdhsa_user_sgpr_dispatch_ptr 0
		.amdhsa_user_sgpr_queue_ptr 0
		.amdhsa_user_sgpr_kernarg_segment_ptr 1
		.amdhsa_user_sgpr_dispatch_id 0
		.amdhsa_user_sgpr_kernarg_preload_length 0
		.amdhsa_user_sgpr_kernarg_preload_offset 0
		.amdhsa_user_sgpr_private_segment_size 0
		.amdhsa_uses_dynamic_stack 0
		.amdhsa_enable_private_segment 0
		.amdhsa_system_sgpr_workgroup_id_x 1
		.amdhsa_system_sgpr_workgroup_id_y 0
		.amdhsa_system_sgpr_workgroup_id_z 0
		.amdhsa_system_sgpr_workgroup_info 0
		.amdhsa_system_vgpr_workitem_id 2
		.amdhsa_next_free_vgpr 256
		.amdhsa_next_free_sgpr 102
		.amdhsa_accum_offset 256
		.amdhsa_reserve_vcc 1
		.amdhsa_float_round_mode_32 0
		.amdhsa_float_round_mode_16_64 0
		.amdhsa_float_denorm_mode_32 3
		.amdhsa_float_denorm_mode_16_64 3
		.amdhsa_dx10_clamp 1
		.amdhsa_ieee_mode 1
		.amdhsa_fp16_overflow 0
		.amdhsa_tg_split 0
		.amdhsa_exception_fp_ieee_invalid_op 0
		.amdhsa_exception_fp_denorm_src 0
		.amdhsa_exception_fp_ieee_div_zero 0
		.amdhsa_exception_fp_ieee_overflow 0
		.amdhsa_exception_fp_ieee_underflow 0
		.amdhsa_exception_fp_ieee_inexact 0
		.amdhsa_exception_int_div_zero 0
	.end_amdhsa_kernel

; #define LAS __attribute__((address_space(3)))
; __global__ void __launch_bounds__(512, 2) fwd_kernel(KP p) {
;     extern __shared__ __attribute__((aligned(16))) unsigned char lds_raw[];
;     LAS unsigned char* lds = (LAS unsigned char*)lds_raw;
;     const int wave = __builtin_amdgcn_readfirstlane((int)threadIdx.x >> 6);
;     const int G = gridDim.x, b = blockIdx.x;
;     const int gw = b * 8 + wave, NGW = G * 8;
;     const int gw2 = wave * G + b;
;     const int NGT = G * 512;
amdhsa.kernels:
  - .agpr_count:     0
    .args:
      - .offset:         0
        .size:           256
        .value_kind:     by_value
      - .offset:         256
        .size:           4
        .value_kind:     hidden_block_count_x
      - .offset:         260
        .size:           4
        .value_kind:     hidden_block_count_y
      - .offset:         264
        .size:           4
        .value_kind:     hidden_block_count_z
      - .offset:         268
        .size:           2
        .value_kind:     hidden_group_size_x
      - .offset:         270
        .size:           2
        .value_kind:     hidden_group_size_y
      - .offset:         272
        .size:           2
        .value_kind:     hidden_group_size_z
      - .offset:         274
        .size:           2
        .value_kind:     hidden_remainder_x
      - .offset:         276
        .size:           2
        .value_kind:     hidden_remainder_y
      - .offset:         278
        .size:           2
        .value_kind:     hidden_remainder_z
      - .offset:         296
        .size:           8
        .value_kind:     hidden_global_offset_x
      - .offset:         304
        .size:           8
        .value_kind:     hidden_global_offset_y
      - .offset:         312
        .size:           8
        .value_kind:     hidden_global_offset_z
      - .offset:         320
        .size:           2
        .value_kind:     hidden_grid_dims
      - .offset:         344
        .size:           8
        .value_kind:     hidden_multigrid_sync_arg
      - .offset:         376
        .size:           4
        .value_kind:     hidden_dynamic_lds_size
    .group_segment_fixed_size: 0
    .kernarg_segment_align: 8
    .kernarg_segment_size: 512
    .language:       OpenCL C
    .language_version:
      - 2
      - 0
    .max_flat_workgroup_size: 512
    .name:           _Z10fwd_kernel2KP
    .private_segment_fixed_size: 0
    .sgpr_count:     108
    .sgpr_spill_count: 168
    .symbol:         _Z10fwd_kernel2KP.kd
    .uniform_work_group_size: 1
    .uses_dynamic_stack: false
    .vgpr_count:     256
    .vgpr_spill_count: 0
    .wavefront_size: 64
